# batched serialized loads: compress K-loop rewrite, cmpsel K/V loads, vtrans P loads, gdn conv pass3
# baseline (speedup 1.0000x reference)
; __device__ __forceinline__ f32x4 mfma16(bf16x8 a, bf16x8 b, f32x4 c) { return __builtin_amdgcn_mfma_f32_16x16x32_bf16(a, b, c, 0, 0, 0); }
; #define WSP(T, off) ((T*)(__attribute__((address_space(1))) T*)(launder_ws(AWS, (off))))
; __device__ __forceinline__ void cmpsel_item(const Args& a, int it, unsigned char* lds, unsigned* cmp_done) {
;     ...
;             { const bf16_t* q = WSP(const bf16_t, WS_QB) + (size_t)(b * SEQ + tokbase + fr) * 768 + (g * 3 + r) * 128 + fq * 8;
; #pragma unroll
;               for (int ks = 0; ks < 4; ++ks) qf[ks] = *(const bf16x8*)(q + ks * 32); }
;             f32x4 S[16];
;             const int tmaxw = __builtin_amdgcn_readfirstlane(tokbase) + 15;
; #pragma unroll
;             for (int g4 = 0; g4 < 4; ++g4) {
; #pragma unroll
;                 for (int n4 = 0; n4 < 4; ++n4) S[g4 * 4 + n4] = zero4();
;                 if (1024 * g4 + 31 <= tmaxw) {
;                     bf16x8 kf[16];
; #pragma unroll
;                     for (int i = 0; i < 16; ++i) kf[i] = *(const bf16x8*)(Kc + (size_t)((g4 * 4 + (i >> 2)) * 16 + fr) * 128 + (i & 3) * 32 + fq * 8);
; #pragma unroll
;                     for (int n4 = 0; n4 < 4; ++n4) {
; #pragma unroll
;                         for (int ks = 0; ks < 4; ++ks) S[g4 * 4 + n4] = mfma16(qf[ks], kf[n4 * 4 + ks], S[g4 * 4 + n4]);
;                     }
;                 }
.LBB0_251:
	v_mov_b32_e32 v91, v83
	s_mov_b64 s[2:3], s[0:1]
	s_load_dwordx2 s[2:3], s[2:3], 0xd0
	s_mov_b64 s[40:41], 0x1dc18000
	v_and_b32_e32 v90, 15, v91
	v_ashrrev_i32_e32 v92, 4, v91
	v_or_b32_e32 v2, v90, v89
	v_lshlrev_b32_e32 v80, 3, v92
	v_mov_b64_e32 v[0:1], s[40:41]
	s_movk_i32 s40, 0x600
	v_ashrrev_i32_e32 v81, 31, v80
	v_mad_i64_i32 v[0:1], s[40:41], v2, s40, v[0:1]
	v_lshl_add_u64 v[0:1], v[80:81], 1, v[0:1]
	s_waitcnt lgkmcnt(0)
	v_lshl_add_u64 v[0:1], s[2:3], 0, v[0:1]
	v_lshl_add_u64 v[0:1], v[0:1], 0, s[38:39]
	global_load_dwordx4 v[76:79], v[0:1], off
	global_load_dwordx4 v[56:59], v[0:1], off offset:64
	global_load_dwordx4 v[52:55], v[0:1], off offset:128
	global_load_dwordx4 v[48:51], v[0:1], off offset:192
	v_readfirstlane_b32 s60, v86
	s_mov_b32 s40, 0
	s_mov_b32 s52, 0
	s_mov_b32 s48, 0
	s_mov_b32 s44, 0
	s_cmp_gt_i32 s60, 15
	s_cselect_b64 s[2:3], -1, 0
	s_cmp_lt_i32 s60, 16
	v_mov_b32_e32 v0, s40
	v_mov_b32_e32 v4, s52
	v_mov_b32_e32 v8, s48
	v_mov_b32_e32 v12, s44
	v_lshlrev_b32_e32 v214, 8, v90
	v_mov_b32_e32 v1, s40
	v_mov_b32_e32 v2, s40
	v_mov_b32_e32 v3, s40
	v_mov_b32_e32 v5, s52
	v_mov_b32_e32 v6, s52
	v_mov_b32_e32 v7, s52
	v_mov_b32_e32 v9, s48
	v_mov_b32_e32 v10, s48
	v_mov_b32_e32 v11, s48
	v_mov_b32_e32 v13, s44
	v_mov_b32_e32 v14, s44
	v_mov_b32_e32 v15, s44
	s_cbranch_scc1 .LBB0_253
	v_lshl_add_u64 v[0:1], s[20:21], 0, v[214:215]
	v_lshl_add_u64 v[20:21], v[80:81], 1, v[0:1]
	global_load_dwordx4 v[120:123], v[20:21], off
	global_load_dwordx4 v[124:127], v[20:21], off offset:64
	v_add_co_u32_e32 v22, vcc, 0x1000, v20
	s_mov_b32 s41, s40
	s_nop 0
	v_addc_co_u32_e32 v23, vcc, 0, v21, vcc
	global_load_dwordx4 v[128:131], v[22:23], off
	s_mov_b32 s42, s40
	s_mov_b32 s43, s40
	v_mov_b64_e32 v[8:9], s[40:41]
	v_mov_b64_e32 v[10:11], s[42:43]
	v_add_co_u32_e32 v24, vcc, s85, v20
	s_movk_i32 s42, 0x3000
	s_mov_b64 s[40:41], vcc
	v_add_co_u32_e32 v26, vcc, s42, v20
	s_mov_b32 s53, s52
	s_nop 0
	v_addc_co_u32_e32 v27, vcc, 0, v21, vcc
	s_mov_b32 s54, s52
	s_mov_b32 s55, s52
	v_mov_b64_e32 v[16:17], s[52:53]
	v_mov_b64_e32 v[18:19], s[54:55]
	s_mov_b32 s49, s48
	s_mov_b32 s50, s48
	s_mov_b32 s51, s48
	s_mov_b32 s45, s44
	s_mov_b32 s46, s44
	s_mov_b32 s47, s44
	v_addc_co_u32_e64 v25, vcc, 0, v21, s[40:41]
	global_load_dwordx4 v[132:135], v[26:27], off offset:-4096
	global_load_dwordx4 v[136:139], v[26:27], off
	global_load_dwordx4 v[140:143], v[22:23], off offset:64
	global_load_dwordx4 v[144:147], v[20:21], off offset:128
	global_load_dwordx4 v[148:151], v[24:25], off offset:64
	global_load_dwordx4 v[152:155], v[26:27], off offset:64
	global_load_dwordx4 v[156:159], v[22:23], off offset:128
	global_load_dwordx4 v[160:163], v[20:21], off offset:192
	global_load_dwordx4 v[164:167], v[24:25], off offset:128
	global_load_dwordx4 v[168:171], v[26:27], off offset:128
	global_load_dwordx4 v[172:175], v[22:23], off offset:192
	global_load_dwordx4 v[176:179], v[24:25], off offset:192
	global_load_dwordx4 v[180:183], v[26:27], off offset:192
	s_nop 0
	s_waitcnt vmcnt(15)
	v_mfma_f32_16x16x32_bf16 v[0:3], v[76:79], v[120:123], v[8:11]
	s_nop 2
	s_nop 0
	s_nop 0
	s_waitcnt vmcnt(13)
	v_mfma_f32_16x16x32_bf16 v[4:7], v[76:79], v[128:131], v[16:19]
	s_nop 2
	s_nop 0
	v_mfma_f32_16x16x32_bf16 v[0:3], v[56:59], v[124:127], v[0:3]
	v_mov_b64_e32 v[12:13], s[48:49]
	v_mov_b64_e32 v[14:15], s[50:51]
	s_nop 0
	s_nop 0
	s_waitcnt vmcnt(12)
	v_mfma_f32_16x16x32_bf16 v[8:11], v[76:79], v[132:135], v[12:15]
	s_nop 2
	v_mov_b64_e32 v[12:13], s[44:45]
	v_mov_b64_e32 v[14:15], s[46:47]
	s_nop 0
	s_nop 0
	s_waitcnt vmcnt(11)
	v_mfma_f32_16x16x32_bf16 v[12:15], v[76:79], v[136:139], v[12:15]
	s_nop 0
	s_nop 0
	s_waitcnt vmcnt(10)
	v_mfma_f32_16x16x32_bf16 v[4:7], v[56:59], v[140:143], v[4:7]
	s_nop 0
	s_nop 0
	s_waitcnt vmcnt(9)
	v_mfma_f32_16x16x32_bf16 v[0:3], v[52:55], v[144:147], v[0:3]
	s_nop 0
	s_nop 0
	s_waitcnt vmcnt(8)
	v_mfma_f32_16x16x32_bf16 v[8:11], v[56:59], v[148:151], v[8:11]
	s_nop 0
	s_nop 0
	s_waitcnt vmcnt(7)
	v_mfma_f32_16x16x32_bf16 v[12:15], v[56:59], v[152:155], v[12:15]
	s_nop 0
	s_nop 0
	s_waitcnt vmcnt(6)
	v_mfma_f32_16x16x32_bf16 v[4:7], v[52:55], v[156:159], v[4:7]
	s_nop 0
	s_nop 0
	s_waitcnt vmcnt(5)
	v_mfma_f32_16x16x32_bf16 v[0:3], v[48:51], v[160:163], v[0:3]
	s_nop 0
	s_nop 0
	s_waitcnt vmcnt(4)
	v_mfma_f32_16x16x32_bf16 v[8:11], v[52:55], v[164:167], v[8:11]
	s_nop 0
	s_nop 0
	s_waitcnt vmcnt(3)
	v_mfma_f32_16x16x32_bf16 v[12:15], v[52:55], v[168:171], v[12:15]
	s_nop 0
	s_nop 0
	s_waitcnt vmcnt(2)
	v_mfma_f32_16x16x32_bf16 v[4:7], v[48:51], v[172:175], v[4:7]
	s_nop 0
	s_nop 0
	s_waitcnt vmcnt(1)
	v_mfma_f32_16x16x32_bf16 v[8:11], v[48:51], v[176:179], v[8:11]
	s_nop 0
	s_nop 0
	s_waitcnt vmcnt(0)
	v_mfma_f32_16x16x32_bf16 v[12:15], v[48:51], v[180:183], v[12:15]
; __device__ __forceinline__ f32x4 mfma16(bf16x8 a, bf16x8 b, f32x4 c) { return __builtin_amdgcn_mfma_f32_16x16x32_bf16(a, b, c, 0, 0, 0); }
; __device__ __forceinline__ void cmpsel_item(const Args& a, int it, unsigned char* lds, unsigned* cmp_done) {
;     ...
;             const int tmaxw = __builtin_amdgcn_readfirstlane(tokbase) + 15;
; #pragma unroll
;             for (int g4 = 0; g4 < 4; ++g4) {
; #pragma unroll
;                 for (int n4 = 0; n4 < 4; ++n4) S[g4 * 4 + n4] = zero4();
;                 if (1024 * g4 + 31 <= tmaxw) {
;                     bf16x8 kf[16];
; #pragma unroll
;                     for (int i = 0; i < 16; ++i) kf[i] = *(const bf16x8*)(Kc + (size_t)((g4 * 4 + (i >> 2)) * 16 + fr) * 128 + (i & 3) * 32 + fq * 8);
; #pragma unroll
;                     for (int n4 = 0; n4 < 4; ++n4) {
; #pragma unroll
;                         for (int ks = 0; ks < 4; ++ks) S[g4 * 4 + n4] = mfma16(qf[ks], kf[n4 * 4 + ks], S[g4 * 4 + n4]);
;                     }
;                 }
.LBB0_253:
	s_mov_b32 s56, 0
	s_mov_b32 s52, 0
	s_mov_b32 s48, 0
	s_mov_b32 s44, 0
	s_mov_b32 s92, s84
	s_cmpk_lt_i32 s60, 0x410
	v_mov_b32_e32 v20, s56
	v_mov_b32_e32 v16, s52
	v_mov_b32_e32 v24, s48
	v_mov_b32_e32 v28, s44
	v_mov_b32_e32 v21, s56
	v_mov_b32_e32 v22, s56
	v_mov_b32_e32 v23, s56
	v_mov_b32_e32 v17, s52
	v_mov_b32_e32 v18, s52
	v_mov_b32_e32 v19, s52
	v_mov_b32_e32 v25, s48
	v_mov_b32_e32 v26, s48
	v_mov_b32_e32 v27, s48
	v_mov_b32_e32 v29, s44
	v_mov_b32_e32 v30, s44
	v_mov_b32_e32 v31, s44
	s_cbranch_scc1 .LBB0_255
	v_lshl_add_u64 v[16:17], s[20:21], 0, v[214:215]
	v_lshl_add_u64 v[36:37], v[80:81], 1, v[16:17]
	v_add_co_u32_e32 v38, vcc, 0x4000, v36
	s_mov_b32 s57, s56
	s_nop 0
	v_addc_co_u32_e32 v39, vcc, 0, v37, vcc
	global_load_dwordx4 v[120:123], v[38:39], off
	v_add_co_u32_e32 v40, vcc, 0x5000, v36
	s_mov_b32 s58, s56
	s_nop 0
	v_addc_co_u32_e32 v41, vcc, 0, v37, vcc
	global_load_dwordx4 v[124:127], v[40:41], off
	v_add_co_u32_e32 v42, vcc, s94, v36
	s_mov_b64 s[40:41], vcc
	v_add_co_u32_e32 v44, vcc, s71, v36
	s_mov_b32 s59, s56
	s_nop 0
	v_addc_co_u32_e32 v45, vcc, 0, v37, vcc
	global_load_dwordx4 v[128:131], v[44:45], off offset:-4096
	global_load_dwordx4 v[132:135], v[44:45], off
	v_mov_b64_e32 v[32:33], s[56:57]
	s_mov_b32 s53, s52
	v_mov_b64_e32 v[34:35], s[58:59]
	s_mov_b32 s54, s52
	s_mov_b32 s55, s52
	s_mov_b32 s49, s48
	s_mov_b32 s50, s48
	s_mov_b32 s51, s48
	s_mov_b32 s45, s44
	s_mov_b32 s46, s44
	s_mov_b32 s47, s44
	v_addc_co_u32_e64 v43, vcc, 0, v37, s[40:41]
	global_load_dwordx4 v[136:139], v[38:39], off offset:64
	global_load_dwordx4 v[140:143], v[40:41], off offset:64
	global_load_dwordx4 v[144:147], v[42:43], off offset:64
	global_load_dwordx4 v[148:151], v[44:45], off offset:64
	global_load_dwordx4 v[152:155], v[38:39], off offset:128
	global_load_dwordx4 v[156:159], v[40:41], off offset:128
	global_load_dwordx4 v[160:163], v[42:43], off offset:128
	global_load_dwordx4 v[164:167], v[44:45], off offset:128
	global_load_dwordx4 v[168:171], v[38:39], off offset:192
	global_load_dwordx4 v[172:175], v[40:41], off offset:192
	global_load_dwordx4 v[176:179], v[42:43], off offset:192
	global_load_dwordx4 v[180:183], v[44:45], off offset:192
	s_nop 0
	s_waitcnt vmcnt(15)
	v_mfma_f32_16x16x32_bf16 v[16:19], v[76:79], v[120:123], v[32:35]
	s_nop 2
	v_mov_b64_e32 v[32:33], s[52:53]
	v_mov_b64_e32 v[34:35], s[54:55]
	s_nop 0
	s_nop 0
	s_waitcnt vmcnt(14)
	v_mfma_f32_16x16x32_bf16 v[20:23], v[76:79], v[124:127], v[32:35]
	s_nop 2
	v_mov_b64_e32 v[32:33], s[48:49]
	v_mov_b64_e32 v[34:35], s[50:51]
	s_nop 0
	s_nop 0
	s_waitcnt vmcnt(13)
	v_mfma_f32_16x16x32_bf16 v[24:27], v[76:79], v[128:131], v[32:35]
	s_nop 2
	v_mov_b64_e32 v[32:33], s[44:45]
	v_mov_b64_e32 v[34:35], s[46:47]
	s_nop 0
	s_nop 0
	s_waitcnt vmcnt(12)
	v_mfma_f32_16x16x32_bf16 v[28:31], v[76:79], v[132:135], v[32:35]
	s_nop 2
	s_nop 0
	s_nop 0
	s_waitcnt vmcnt(11)
	v_mfma_f32_16x16x32_bf16 v[16:19], v[56:59], v[136:139], v[16:19]
	s_nop 0
	s_nop 0
	s_waitcnt vmcnt(10)
	v_mfma_f32_16x16x32_bf16 v[20:23], v[56:59], v[140:143], v[20:23]
	s_nop 0
	s_nop 0
	s_waitcnt vmcnt(9)
	v_mfma_f32_16x16x32_bf16 v[24:27], v[56:59], v[144:147], v[24:27]
	s_nop 0
	s_nop 0
	s_waitcnt vmcnt(8)
	v_mfma_f32_16x16x32_bf16 v[28:31], v[56:59], v[148:151], v[28:31]
	s_nop 0
	s_nop 0
	s_waitcnt vmcnt(7)
	v_mfma_f32_16x16x32_bf16 v[16:19], v[52:55], v[152:155], v[16:19]
	s_nop 0
	s_nop 0
	s_waitcnt vmcnt(6)
	v_mfma_f32_16x16x32_bf16 v[32:35], v[52:55], v[156:159], v[20:23]
	s_nop 2
	s_nop 0
	s_nop 0
	s_waitcnt vmcnt(5)
	v_mfma_f32_16x16x32_bf16 v[24:27], v[52:55], v[160:163], v[24:27]
	s_nop 0
	s_nop 0
	s_waitcnt vmcnt(4)
	v_mfma_f32_16x16x32_bf16 v[28:31], v[52:55], v[164:167], v[28:31]
	s_nop 0
	s_nop 0
	s_waitcnt vmcnt(3)
	v_mfma_f32_16x16x32_bf16 v[20:23], v[48:51], v[168:171], v[16:19]
	s_nop 2
	s_nop 0
	s_nop 0
	s_waitcnt vmcnt(2)
	v_mfma_f32_16x16x32_bf16 v[16:19], v[48:51], v[172:175], v[32:35]
	s_nop 2
	s_nop 0
	s_nop 0
	s_waitcnt vmcnt(1)
	v_mfma_f32_16x16x32_bf16 v[24:27], v[48:51], v[176:179], v[24:27]
	s_nop 0
	s_nop 0
	s_waitcnt vmcnt(0)
	v_mfma_f32_16x16x32_bf16 v[28:31], v[48:51], v[180:183], v[28:31]
.LBB0_255:
	s_mov_b32 s52, 0
	s_mov_b32 s48, 0
	s_mov_b32 s44, 0
	s_mov_b32 s40, 0
	s_cmpk_gt_i32 s60, 0x80f
	s_cselect_b64 s[84:85], -1, 0
	s_cmpk_lt_i32 s60, 0x810
	v_mov_b32_e32 v32, s52
	v_mov_b32_e32 v36, s48
	v_mov_b32_e32 v40, s44
	v_mov_b32_e32 v44, s40
	v_mov_b32_e32 v33, s52
	v_mov_b32_e32 v34, s52
	v_mov_b32_e32 v35, s52
	v_mov_b32_e32 v37, s48
	v_mov_b32_e32 v38, s48
	v_mov_b32_e32 v39, s48
	v_mov_b32_e32 v41, s44
	v_mov_b32_e32 v42, s44
	v_mov_b32_e32 v43, s44
	v_mov_b32_e32 v45, s40
	v_mov_b32_e32 v46, s40
	v_mov_b32_e32 v47, s40
	s_cbranch_scc1 .LBB0_257
; __device__ __forceinline__ f32x4 mfma16(bf16x8 a, bf16x8 b, f32x4 c) { return __builtin_amdgcn_mfma_f32_16x16x32_bf16(a, b, c, 0, 0, 0); }
; __device__ __forceinline__ void cmpsel_item(const Args& a, int it, unsigned char* lds, unsigned* cmp_done) {
;     ...
;             const int tmaxw = __builtin_amdgcn_readfirstlane(tokbase) + 15;
; #pragma unroll
;             for (int g4 = 0; g4 < 4; ++g4) {
; #pragma unroll
;                 for (int n4 = 0; n4 < 4; ++n4) S[g4 * 4 + n4] = zero4();
;                 if (1024 * g4 + 31 <= tmaxw) {
;                     bf16x8 kf[16];
; #pragma unroll
;                     for (int i = 0; i < 16; ++i) kf[i] = *(const bf16x8*)(Kc + (size_t)((g4 * 4 + (i >> 2)) * 16 + fr) * 128 + (i & 3) * 32 + fq * 8);
; #pragma unroll
;                     for (int n4 = 0; n4 < 4; ++n4) {
; #pragma unroll
;                         for (int ks = 0; ks < 4; ++ks) S[g4 * 4 + n4] = mfma16(qf[ks], kf[n4 * 4 + ks], S[g4 * 4 + n4]);
;                     }
;                 }
	v_lshl_add_u64 v[32:33], s[20:21], 0, v[214:215]
	v_lshl_add_u64 v[44:45], v[80:81], 1, v[32:33]
	v_add_co_u32_e32 v64, vcc, 0x8000, v44
	s_mov_b32 s41, 0xa000
	s_nop 0
	v_addc_co_u32_e32 v65, vcc, 0, v45, vcc
	global_load_dwordx4 v[120:123], v[64:65], off
	v_add_co_u32_e32 v66, vcc, 0x9000, v44
	s_mov_b32 s54, s52
	s_nop 0
	v_addc_co_u32_e32 v67, vcc, 0, v45, vcc
	global_load_dwordx4 v[124:127], v[66:67], off
	v_add_co_u32_e32 v68, vcc, s41, v44
	s_mov_b32 s55, s52
	s_nop 0
	v_addc_co_u32_e32 v69, vcc, 0, v45, vcc
	global_load_dwordx4 v[128:131], v[68:69], off
	v_add_co_u32_e32 v70, vcc, 0xb000, v44
	s_mov_b32 s53, s52
	s_nop 0
	v_addc_co_u32_e32 v71, vcc, 0, v45, vcc
	global_load_dwordx4 v[132:135], v[70:71], off
	v_mov_b64_e32 v[62:63], s[54:55]
	s_mov_b32 s50, s48
	s_mov_b32 s51, s48
	v_mov_b64_e32 v[60:61], s[52:53]
	s_mov_b32 s49, s48
	s_mov_b32 s46, s44
	s_mov_b32 s47, s44
	s_mov_b32 s45, s44
	s_mov_b32 s42, s40
	s_mov_b32 s43, s40
	s_mov_b32 s41, s40
	global_load_dwordx4 v[136:139], v[64:65], off offset:64
	global_load_dwordx4 v[140:143], v[66:67], off offset:64
	global_load_dwordx4 v[144:147], v[68:69], off offset:64
	global_load_dwordx4 v[148:151], v[70:71], off offset:64
	global_load_dwordx4 v[152:155], v[64:65], off offset:128
	global_load_dwordx4 v[156:159], v[66:67], off offset:128
	global_load_dwordx4 v[160:163], v[68:69], off offset:128
	global_load_dwordx4 v[164:167], v[70:71], off offset:128
	global_load_dwordx4 v[168:171], v[64:65], off offset:192
	global_load_dwordx4 v[172:175], v[66:67], off offset:192
	global_load_dwordx4 v[176:179], v[68:69], off offset:192
	global_load_dwordx4 v[180:183], v[70:71], off offset:192
	s_nop 0
	s_waitcnt vmcnt(15)
	v_mfma_f32_16x16x32_bf16 v[32:35], v[76:79], v[120:123], v[60:63]
	s_nop 2
	v_mov_b64_e32 v[62:63], s[50:51]
	v_mov_b64_e32 v[60:61], s[48:49]
	s_nop 0
	s_nop 0
	s_waitcnt vmcnt(14)
	v_mfma_f32_16x16x32_bf16 v[36:39], v[76:79], v[124:127], v[60:63]
	s_nop 2
	v_mov_b64_e32 v[62:63], s[46:47]
	v_mov_b64_e32 v[60:61], s[44:45]
	s_nop 0
	s_nop 0
	s_waitcnt vmcnt(13)
	v_mfma_f32_16x16x32_bf16 v[40:43], v[76:79], v[128:131], v[60:63]
	s_nop 2
	v_mov_b64_e32 v[62:63], s[42:43]
	v_mov_b64_e32 v[60:61], s[40:41]
	s_nop 0
	s_nop 0
	s_waitcnt vmcnt(12)
	v_mfma_f32_16x16x32_bf16 v[44:47], v[76:79], v[132:135], v[60:63]
	s_nop 2
	s_nop 0
	s_nop 0
	s_waitcnt vmcnt(11)
	v_mfma_f32_16x16x32_bf16 v[32:35], v[56:59], v[136:139], v[32:35]
	s_nop 0
	s_nop 0
	s_waitcnt vmcnt(10)
	v_mfma_f32_16x16x32_bf16 v[36:39], v[56:59], v[140:143], v[36:39]
	s_nop 0
	s_nop 0
	s_waitcnt vmcnt(9)
	v_mfma_f32_16x16x32_bf16 v[40:43], v[56:59], v[144:147], v[40:43]
	s_nop 0
	s_nop 0
	s_waitcnt vmcnt(8)
	v_mfma_f32_16x16x32_bf16 v[44:47], v[56:59], v[148:151], v[44:47]
	s_nop 0
	s_nop 0
	s_waitcnt vmcnt(7)
	v_mfma_f32_16x16x32_bf16 v[32:35], v[52:55], v[152:155], v[32:35]
	s_nop 0
	s_nop 0
	s_waitcnt vmcnt(6)
	v_mfma_f32_16x16x32_bf16 v[36:39], v[52:55], v[156:159], v[36:39]
	s_nop 0
	s_nop 0
	s_waitcnt vmcnt(5)
	v_mfma_f32_16x16x32_bf16 v[40:43], v[52:55], v[160:163], v[40:43]
	s_nop 0
	s_nop 0
	s_waitcnt vmcnt(4)
	v_mfma_f32_16x16x32_bf16 v[44:47], v[52:55], v[164:167], v[44:47]
	s_nop 0
	s_nop 0
	s_waitcnt vmcnt(3)
	v_mfma_f32_16x16x32_bf16 v[32:35], v[48:51], v[168:171], v[32:35]
	s_nop 0
	s_nop 0
	s_waitcnt vmcnt(2)
	v_mfma_f32_16x16x32_bf16 v[36:39], v[48:51], v[172:175], v[36:39]
	s_nop 0
	s_nop 0
	s_waitcnt vmcnt(1)
	v_mfma_f32_16x16x32_bf16 v[40:43], v[48:51], v[176:179], v[40:43]
	s_nop 0
	s_nop 0
	s_waitcnt vmcnt(0)
	v_mfma_f32_16x16x32_bf16 v[44:47], v[48:51], v[180:183], v[44:47]
; __device__ __forceinline__ f32x4 mfma16(bf16x8 a, bf16x8 b, f32x4 c) { return __builtin_amdgcn_mfma_f32_16x16x32_bf16(a, b, c, 0, 0, 0); }
; __device__ __forceinline__ void cmpsel_item(const Args& a, int it, unsigned char* lds, unsigned* cmp_done) {
;     ...
;             const int tmaxw = __builtin_amdgcn_readfirstlane(tokbase) + 15;
; #pragma unroll
;             for (int g4 = 0; g4 < 4; ++g4) {
; #pragma unroll
;                 for (int n4 = 0; n4 < 4; ++n4) S[g4 * 4 + n4] = zero4();
;                 if (1024 * g4 + 31 <= tmaxw) {
;                     bf16x8 kf[16];
; #pragma unroll
;                     for (int i = 0; i < 16; ++i) kf[i] = *(const bf16x8*)(Kc + (size_t)((g4 * 4 + (i >> 2)) * 16 + fr) * 128 + (i & 3) * 32 + fq * 8);
; #pragma unroll
;                     for (int n4 = 0; n4 < 4; ++n4) {
; #pragma unroll
;                         for (int ks = 0; ks < 4; ++ks) S[g4 * 4 + n4] = mfma16(qf[ks], kf[n4 * 4 + ks], S[g4 * 4 + n4]);
;                     }
;                 }
.LBB0_257:
	s_mov_b32 s52, 0
	s_mov_b32 s48, 0
	s_mov_b32 s44, 0
	s_mov_b32 s40, 0
	s_cmpk_lt_i32 s60, 0xc10
	v_mov_b32_e32 v60, s52
	v_mov_b32_e32 v64, s48
	v_mov_b32_e32 v68, s44
	v_mov_b32_e32 v72, s40
	v_mov_b32_e32 v61, s52
	v_mov_b32_e32 v62, s52
	v_mov_b32_e32 v63, s52
	v_mov_b32_e32 v65, s48
	v_mov_b32_e32 v66, s48
	v_mov_b32_e32 v67, s48
	v_mov_b32_e32 v69, s44
	v_mov_b32_e32 v70, s44
	v_mov_b32_e32 v71, s44
	v_mov_b32_e32 v73, s40
	v_mov_b32_e32 v74, s40
	v_mov_b32_e32 v75, s40
	s_cbranch_scc1 .LBB0_259
	v_lshl_add_u64 v[60:61], s[20:21], 0, v[214:215]
	v_lshl_add_u64 v[72:73], v[80:81], 1, v[60:61]
	v_add_co_u32_e32 v98, vcc, 0xc000, v72
	s_mov_b32 s41, 0xe000
	s_nop 0
	v_addc_co_u32_e32 v99, vcc, 0, v73, vcc
	global_load_dwordx4 v[120:123], v[98:99], off
	v_add_co_u32_e32 v100, vcc, 0xd000, v72
	s_mov_b32 s54, s52
	s_nop 0
	v_addc_co_u32_e32 v101, vcc, 0, v73, vcc
	global_load_dwordx4 v[124:127], v[100:101], off
	v_add_co_u32_e32 v102, vcc, s41, v72
	s_mov_b32 s55, s52
	s_nop 0
	v_addc_co_u32_e32 v103, vcc, 0, v73, vcc
	global_load_dwordx4 v[128:131], v[102:103], off
	v_add_co_u32_e32 v104, vcc, 0xf000, v72
	s_mov_b32 s53, s52
	s_nop 0
	v_addc_co_u32_e32 v105, vcc, 0, v73, vcc
	global_load_dwordx4 v[132:135], v[104:105], off
	v_mov_b64_e32 v[96:97], s[54:55]
	s_mov_b32 s50, s48
	s_mov_b32 s51, s48
	v_mov_b64_e32 v[94:95], s[52:53]
	s_mov_b32 s49, s48
	s_mov_b32 s46, s44
	s_mov_b32 s47, s44
	s_mov_b32 s45, s44
	s_mov_b32 s42, s40
	s_mov_b32 s43, s40
	s_mov_b32 s41, s40
	global_load_dwordx4 v[136:139], v[98:99], off offset:64
	global_load_dwordx4 v[140:143], v[100:101], off offset:64
	global_load_dwordx4 v[144:147], v[102:103], off offset:64
	global_load_dwordx4 v[148:151], v[104:105], off offset:64
	global_load_dwordx4 v[152:155], v[98:99], off offset:128
	global_load_dwordx4 v[156:159], v[100:101], off offset:128
	global_load_dwordx4 v[160:163], v[102:103], off offset:128
	global_load_dwordx4 v[164:167], v[104:105], off offset:128
	global_load_dwordx4 v[168:171], v[98:99], off offset:192
	global_load_dwordx4 v[172:175], v[100:101], off offset:192
	global_load_dwordx4 v[176:179], v[102:103], off offset:192
	global_load_dwordx4 v[180:183], v[104:105], off offset:192
	s_nop 0
	s_waitcnt vmcnt(15)
	v_mfma_f32_16x16x32_bf16 v[60:63], v[76:79], v[120:123], v[94:97]
	s_nop 2
	v_mov_b64_e32 v[96:97], s[50:51]
	v_mov_b64_e32 v[94:95], s[48:49]
	s_nop 0
	s_nop 0
	s_waitcnt vmcnt(14)
	v_mfma_f32_16x16x32_bf16 v[64:67], v[76:79], v[124:127], v[94:97]
	s_nop 2
	v_mov_b64_e32 v[96:97], s[46:47]
	v_mov_b64_e32 v[94:95], s[44:45]
	s_nop 0
	s_nop 0
	s_waitcnt vmcnt(13)
	v_mfma_f32_16x16x32_bf16 v[68:71], v[76:79], v[128:131], v[94:97]
	s_nop 2
	v_mov_b64_e32 v[96:97], s[42:43]
	v_mov_b64_e32 v[94:95], s[40:41]
	s_nop 0
	s_nop 0
	s_waitcnt vmcnt(12)
	v_mfma_f32_16x16x32_bf16 v[72:75], v[76:79], v[132:135], v[94:97]
	s_nop 0
	s_nop 0
	s_waitcnt vmcnt(11)
	v_mfma_f32_16x16x32_bf16 v[60:63], v[56:59], v[136:139], v[60:63]
	s_nop 0
	s_nop 0
	s_waitcnt vmcnt(10)
	v_mfma_f32_16x16x32_bf16 v[64:67], v[56:59], v[140:143], v[64:67]
	s_nop 0
	s_nop 0
	s_waitcnt vmcnt(9)
	v_mfma_f32_16x16x32_bf16 v[68:71], v[56:59], v[144:147], v[68:71]
	s_nop 0
	s_nop 0
	s_waitcnt vmcnt(8)
	v_mfma_f32_16x16x32_bf16 v[56:59], v[56:59], v[148:151], v[72:75]
	s_nop 2
	s_nop 0
	s_nop 0
	s_waitcnt vmcnt(7)
	v_mfma_f32_16x16x32_bf16 v[60:63], v[52:55], v[152:155], v[60:63]
	s_nop 0
	s_nop 0
	s_waitcnt vmcnt(6)
	v_mfma_f32_16x16x32_bf16 v[64:67], v[52:55], v[156:159], v[64:67]
	s_nop 0
	s_nop 0
	s_waitcnt vmcnt(5)
	v_mfma_f32_16x16x32_bf16 v[68:71], v[52:55], v[160:163], v[68:71]
	s_nop 0
	s_nop 0
	s_waitcnt vmcnt(4)
	v_mfma_f32_16x16x32_bf16 v[52:55], v[52:55], v[164:167], v[56:59]
	s_nop 2
	s_nop 0
	s_nop 0
	s_waitcnt vmcnt(3)
	v_mfma_f32_16x16x32_bf16 v[60:63], v[48:51], v[168:171], v[60:63]
	s_nop 0
	s_nop 0
	s_waitcnt vmcnt(2)
	v_mfma_f32_16x16x32_bf16 v[64:67], v[48:51], v[172:175], v[64:67]
	s_nop 0
	s_nop 0
	s_waitcnt vmcnt(1)
	v_mfma_f32_16x16x32_bf16 v[68:71], v[48:51], v[176:179], v[68:71]
	s_nop 0
	s_nop 0
	s_waitcnt vmcnt(0)
	v_mfma_f32_16x16x32_bf16 v[72:75], v[48:51], v[180:183], v[52:55]

; __device__ __forceinline__ f32x4 mfma16(bf16x8 a, bf16x8 b, f32x4 c) { return __builtin_amdgcn_mfma_f32_16x16x32_bf16(a, b, c, 0, 0, 0); }
; __device__ __forceinline__ void cmpsel_item(const Args& a, int it, unsigned char* lds, unsigned* cmp_done) {
;     ...
;             float gcv[4];
; #pragma unroll
;             for (int j = 0; j < 4; ++j) gcv[j] = GT[(size_t)(b * SEQ + tokbase + fq * 4 + j) * 32 + g * 9 + r * 3 + 0];
; #pragma unroll
;             for (int dt = 0; dt < 8; ++dt) Oc[dt] = zero4();
; #pragma unroll
;             for (int half = 0; half < 2; ++half)
; #pragma unroll
;                 for (int kg = 0; kg < 2; ++kg) {
;                     if (2048 * kg + 31 > tmaxw) continue;
;                     bf16x8 vf[16];
; #pragma unroll
;                     for (int i = 0; i < 16; ++i) vf[i] = *(const bf16x8*)(Vc + (size_t)((half * 4 + (i & 3)) * 16 + fr) * 256 + (kg * 4 + (i >> 2)) * 32 + fq * 8);
; #pragma unroll
;                     for (int k4 = 0; k4 < 4; ++k4) {
;                         const bf16x8 av = *(const bf16x8*)(Pc + fr * 264 + (kg * 4 + k4) * 32 + fq * 8);
; #pragma unroll
;                         for (int dt = 0; dt < 4; ++dt) Oc[half * 4 + dt] = mfma16(av, vf[k4 * 4 + dt], Oc[half * 4 + dt]);
;                     }
;                 }
.LBB0_515:
	s_or_b64 exec, exec, s[46:47]
	v_add_u32_e32 v32, v76, v89
	v_ashrrev_i32_e32 v33, 31, v32
	s_waitcnt lgkmcnt(0)
	v_lshlrev_b64 v[0:1], 7, v[32:33]
	v_lshl_add_u64 v[0:1], s[24:25], 0, v[0:1]
	global_load_dword v44, v[0:1], off offset:-256
	global_load_dword v43, v[0:1], off offset:-128
	global_load_dword v42, v[0:1], off
	global_load_dword v33, v[0:1], off offset:128
	s_mov_b32 s68, 0
	s_mov_b32 s80, 0
	s_mov_b32 s64, 0
	s_mov_b32 s60, 0
	v_mul_u32_u24_e32 v0, 0x210, v90
	v_lshlrev_b32_e32 v1, 1, v80
	s_mov_b32 s69, s68
	s_mov_b32 s81, s80
	s_mov_b32 s65, s64
	s_mov_b32 s61, s60
	v_add3_u32 v45, v88, v0, v1
	v_cndmask_b32_e64 v0, 0, 1, s[2:3]
	s_mov_b32 s70, s68
	s_mov_b32 s71, s68
	s_mov_b32 s82, s80
	s_mov_b32 s83, s80
	s_mov_b32 s66, s64
	s_mov_b32 s67, s64
	s_mov_b32 s62, s60
	s_mov_b32 s63, s60
	v_cmp_ne_u32_e64 s[40:41], 1, v0
	v_mov_b64_e32 v[8:9], s[68:69]
	v_mov_b64_e32 v[0:1], s[80:81]
	v_mov_b64_e32 v[4:5], s[64:65]
	v_mov_b64_e32 v[12:13], s[60:61]
	s_mov_b32 s52, 0
	s_mov_b32 s56, 0
	s_mov_b32 s48, 0
	s_mov_b32 s44, 0
	s_andn2_b64 vcc, exec, s[2:3]
	v_mov_b64_e32 v[10:11], s[70:71]
	v_mov_b64_e32 v[2:3], s[82:83]
	v_mov_b64_e32 v[6:7], s[66:67]
	v_mov_b64_e32 v[14:15], s[62:63]
	v_lshlrev_b32_e32 v214, 9, v90
	v_lshlrev_b64 v[34:35], 1, v[80:81]
	v_lshlrev_b32_e32 v20, 9, v57
	v_lshlrev_b32_e32 v18, 9, v58
	v_lshlrev_b32_e32 v16, 9, v59
	s_cbranch_vccnz .LBB0_517
	v_mov_b32_e32 v19, v215
	v_lshl_add_u64 v[8:9], s[22:23], 0, v[18:19]
	v_lshl_add_u64 v[46:47], v[8:9], 0, v[34:35]
	global_load_dwordx4 v[120:123], v[46:47], off
	ds_read_b128 v[12:15], v45
	ds_read_b128 v[36:39], v45 offset:64
	v_lshl_add_u64 v[0:1], s[22:23], 0, v[214:215]
	v_lshl_add_u64 v[30:31], v[0:1], 0, v[34:35]
	global_load_dwordx4 v[124:127], v[30:31], off
	v_mov_b32_e32 v17, v215
	v_lshl_add_u64 v[26:27], s[22:23], 0, v[16:17]
	v_lshl_add_u64 v[62:63], v[26:27], 0, v[34:35]
	v_mov_b64_e32 v[26:27], s[64:65]
	v_mov_b64_e32 v[28:29], s[66:67]
	v_mov_b64_e32 v[22:23], s[68:69]
	v_mov_b64_e32 v[24:25], s[70:71]
	v_mov_b32_e32 v21, v215
	v_lshl_add_u64 v[4:5], s[22:23], 0, v[20:21]
	v_lshl_add_u64 v[40:41], v[4:5], 0, v[34:35]
	global_load_dwordx4 v[128:131], v[40:41], off
	v_mov_b64_e32 v[58:59], s[60:61]
	v_mov_b64_e32 v[60:61], s[62:63]
	global_load_dwordx4 v[132:135], v[30:31], off offset:64
	global_load_dwordx4 v[136:139], v[46:47], off offset:64
	global_load_dwordx4 v[140:143], v[30:31], off offset:128
	global_load_dwordx4 v[144:147], v[62:63], off
	global_load_dwordx4 v[148:151], v[40:41], off offset:64
	global_load_dwordx4 v[152:155], v[46:47], off offset:128
	global_load_dwordx4 v[156:159], v[30:31], off offset:192
	global_load_dwordx4 v[160:163], v[62:63], off offset:64
	global_load_dwordx4 v[164:167], v[40:41], off offset:128
	global_load_dwordx4 v[168:171], v[62:63], off offset:128
	global_load_dwordx4 v[172:175], v[40:41], off offset:192
	global_load_dwordx4 v[176:179], v[46:47], off offset:192
	global_load_dwordx4 v[180:183], v[62:63], off offset:192
	s_waitcnt lgkmcnt(1)
	s_waitcnt vmcnt(15)
	v_mfma_f32_16x16x32_bf16 v[8:11], v[12:15], v[120:123], v[26:29]
	s_nop 2
	s_nop 0
	s_nop 0
	s_waitcnt vmcnt(14)
	v_mfma_f32_16x16x32_bf16 v[0:3], v[12:15], v[124:127], v[22:25]
	s_nop 2
	v_mov_b64_e32 v[22:23], s[80:81]
	v_mov_b64_e32 v[24:25], s[82:83]
	s_waitcnt lgkmcnt(0)
	s_waitcnt vmcnt(12)
	v_mfma_f32_16x16x32_bf16 v[0:3], v[36:39], v[132:135], v[0:3]
	s_nop 0
	s_nop 0
	s_waitcnt vmcnt(11)
	v_mfma_f32_16x16x32_bf16 v[8:11], v[36:39], v[136:139], v[8:11]
	s_nop 0
	v_mfma_f32_16x16x32_bf16 v[4:7], v[12:15], v[128:131], v[22:25]
	s_nop 2
	s_nop 0
	s_nop 0
	s_waitcnt vmcnt(9)
	v_mfma_f32_16x16x32_bf16 v[12:15], v[12:15], v[144:147], v[58:61]
	s_nop 2
	ds_read_b128 v[58:61], v45 offset:128
	s_nop 0
	s_waitcnt lgkmcnt(0)
	v_mfma_f32_16x16x32_bf16 v[0:3], v[58:61], v[140:143], v[0:3]
	s_nop 0
	s_nop 0
	s_waitcnt vmcnt(7)
	v_mfma_f32_16x16x32_bf16 v[26:29], v[58:61], v[152:155], v[8:11]
	s_nop 2
	s_nop 0
	v_mfma_f32_16x16x32_bf16 v[4:7], v[36:39], v[148:151], v[4:7]
	s_nop 0
	s_nop 0
	s_waitcnt vmcnt(5)
	v_mfma_f32_16x16x32_bf16 v[12:15], v[36:39], v[160:163], v[12:15]
	s_nop 0
	s_nop 0
	s_waitcnt vmcnt(4)
	v_mfma_f32_16x16x32_bf16 v[4:7], v[58:61], v[164:167], v[4:7]
	s_nop 0
	s_nop 0
	s_waitcnt vmcnt(3)
	v_mfma_f32_16x16x32_bf16 v[12:15], v[58:61], v[168:171], v[12:15]
	ds_read_b128 v[22:25], v45 offset:192
	s_waitcnt lgkmcnt(0)
	v_mfma_f32_16x16x32_bf16 v[8:11], v[22:25], v[156:159], v[0:3]
	s_nop 2
	s_nop 0
	s_nop 0
	s_waitcnt vmcnt(2)
	v_mfma_f32_16x16x32_bf16 v[0:3], v[22:25], v[172:175], v[4:7]
	s_nop 2
	s_nop 0
	s_nop 0
	s_waitcnt vmcnt(1)
	v_mfma_f32_16x16x32_bf16 v[4:7], v[22:25], v[176:179], v[26:29]
	s_nop 2
	s_nop 0
	s_nop 0
	s_waitcnt vmcnt(0)
	v_mfma_f32_16x16x32_bf16 v[12:15], v[22:25], v[180:183], v[12:15]
; __device__ __forceinline__ f32x4 mfma16(bf16x8 a, bf16x8 b, f32x4 c) { return __builtin_amdgcn_mfma_f32_16x16x32_bf16(a, b, c, 0, 0, 0); }
; __device__ __forceinline__ void cmpsel_item(const Args& a, int it, unsigned char* lds, unsigned* cmp_done) {
;     ...
;             for (int half = 0; half < 2; ++half)
; #pragma unroll
;                 for (int kg = 0; kg < 2; ++kg) {
;                     if (2048 * kg + 31 > tmaxw) continue;
;                     bf16x8 vf[16];
; #pragma unroll
;                     for (int i = 0; i < 16; ++i) vf[i] = *(const bf16x8*)(Vc + (size_t)((half * 4 + (i & 3)) * 16 + fr) * 256 + (kg * 4 + (i >> 2)) * 32 + fq * 8);
; #pragma unroll
;                     for (int k4 = 0; k4 < 4; ++k4) {
;                         const bf16x8 av = *(const bf16x8*)(Pc + fr * 264 + (kg * 4 + k4) * 32 + fq * 8);
; #pragma unroll
;                         for (int dt = 0; dt < 4; ++dt) Oc[half * 4 + dt] = mfma16(av, vf[k4 * 4 + dt], Oc[half * 4 + dt]);
;                     }
;                 }
.LBB0_517:
	v_cndmask_b32_e64 v17, 0, 1, s[84:85]
	v_cmp_ne_u32_e64 s[42:43], 1, v17
	s_andn2_b64 vcc, exec, s[84:85]
	s_cbranch_vccnz .LBB0_519
	v_mov_b32_e32 v21, v215
	v_mov_b32_e32 v19, v215
	v_lshl_add_u64 v[22:23], s[22:23], 0, v[214:215]
	v_lshl_add_u64 v[20:21], s[22:23], 0, v[20:21]
	v_lshl_add_u64 v[18:19], s[22:23], 0, v[18:19]
	v_lshl_add_u64 v[30:31], v[22:23], 0, v[34:35]
	v_lshl_add_u64 v[40:41], v[20:21], 0, v[34:35]
	v_lshl_add_u64 v[46:47], v[18:19], 0, v[34:35]
	global_load_dwordx4 v[120:123], v[30:31], off offset:256
	global_load_dwordx4 v[124:127], v[40:41], off offset:256
	global_load_dwordx4 v[128:131], v[46:47], off offset:256
	ds_read_b128 v[36:39], v45 offset:256
	v_mov_b32_e32 v17, v215
	v_lshl_add_u64 v[16:17], s[22:23], 0, v[16:17]
	v_lshl_add_u64 v[58:59], v[16:17], 0, v[34:35]
	global_load_dwordx4 v[132:135], v[30:31], off offset:320
	global_load_dwordx4 v[136:139], v[58:59], off offset:256
	global_load_dwordx4 v[140:143], v[40:41], off offset:320
	global_load_dwordx4 v[144:147], v[46:47], off offset:320
	global_load_dwordx4 v[148:151], v[30:31], off offset:384
	global_load_dwordx4 v[152:155], v[58:59], off offset:320
	global_load_dwordx4 v[156:159], v[46:47], off offset:384
	global_load_dwordx4 v[160:163], v[40:41], off offset:384
	global_load_dwordx4 v[164:167], v[30:31], off offset:448
	global_load_dwordx4 v[168:171], v[58:59], off offset:384
	global_load_dwordx4 v[172:175], v[40:41], off offset:448
	global_load_dwordx4 v[176:179], v[46:47], off offset:448
	global_load_dwordx4 v[180:183], v[58:59], off offset:448
	s_waitcnt lgkmcnt(0)
	s_waitcnt vmcnt(13)
	v_mfma_f32_16x16x32_bf16 v[4:7], v[36:39], v[128:131], v[4:7]
	s_nop 0
	v_mfma_f32_16x16x32_bf16 v[8:11], v[36:39], v[120:123], v[8:11]
	s_nop 0
	v_mfma_f32_16x16x32_bf16 v[0:3], v[36:39], v[124:127], v[0:3]
	ds_read_b128 v[26:29], v45 offset:320
	s_nop 0
	s_waitcnt vmcnt(11)
	v_mfma_f32_16x16x32_bf16 v[12:15], v[36:39], v[136:139], v[12:15]
	s_nop 0
	ds_read_b128 v[36:39], v45 offset:384
	s_waitcnt lgkmcnt(1)
	v_mfma_f32_16x16x32_bf16 v[8:11], v[26:29], v[132:135], v[8:11]
	s_nop 0
	s_nop 0
	s_waitcnt vmcnt(9)
	v_mfma_f32_16x16x32_bf16 v[4:7], v[26:29], v[144:147], v[4:7]
	s_nop 0
	v_mfma_f32_16x16x32_bf16 v[0:3], v[26:29], v[140:143], v[0:3]
	s_nop 0
	s_waitcnt lgkmcnt(0)
	s_waitcnt vmcnt(8)
	v_mfma_f32_16x16x32_bf16 v[8:11], v[36:39], v[148:151], v[8:11]
	s_nop 0
	s_nop 0
	s_waitcnt vmcnt(7)
	v_mfma_f32_16x16x32_bf16 v[12:15], v[26:29], v[152:155], v[12:15]
	s_nop 0
	s_nop 0
	s_waitcnt vmcnt(6)
	v_mfma_f32_16x16x32_bf16 v[4:7], v[36:39], v[156:159], v[4:7]
	s_nop 0
	s_nop 0
	s_waitcnt vmcnt(5)
	v_mfma_f32_16x16x32_bf16 v[0:3], v[36:39], v[160:163], v[0:3]
	s_nop 0
	s_nop 0
	s_waitcnt vmcnt(3)
	v_mfma_f32_16x16x32_bf16 v[12:15], v[36:39], v[168:171], v[12:15]
	ds_read_b128 v[20:23], v45 offset:448
	s_waitcnt lgkmcnt(0)
	v_mfma_f32_16x16x32_bf16 v[8:11], v[20:23], v[164:167], v[8:11]
	s_nop 0
	s_nop 0
	s_waitcnt vmcnt(2)
	v_mfma_f32_16x16x32_bf16 v[0:3], v[20:23], v[172:175], v[0:3]
	s_nop 0
	s_nop 0
	s_waitcnt vmcnt(1)
	v_mfma_f32_16x16x32_bf16 v[4:7], v[20:23], v[176:179], v[4:7]
	s_nop 0
	s_nop 0
	s_waitcnt vmcnt(0)
	v_mfma_f32_16x16x32_bf16 v[12:15], v[20:23], v[180:183], v[12:15]
.LBB0_519:
	s_mov_b32 s53, s52
	s_mov_b32 s57, s56
	s_mov_b32 s49, s48
	s_mov_b32 s45, s44
	s_mov_b32 s54, s52
	s_mov_b32 s55, s52
	s_mov_b32 s58, s56
	s_mov_b32 s59, s56
	s_mov_b32 s50, s48
	s_mov_b32 s51, s48
	s_mov_b32 s46, s44
	s_mov_b32 s47, s44
	v_mov_b64_e32 v[24:25], s[52:53]
	v_mov_b64_e32 v[16:17], s[56:57]
	v_mov_b64_e32 v[20:21], s[48:49]
	v_mov_b64_e32 v[28:29], s[44:45]
	s_mov_b32 s84, s92
	s_movk_i32 s85, 0x2000
	s_movk_i32 s65, 0x80
	s_movk_i32 s69, 0x4000
	s_movk_i32 s70, 0x1000
	s_movk_i32 s71, 0x7000
	s_movk_i32 s66, 0x7f
	s_movk_i32 s67, 0x1fff
	s_mov_b32 s62, 0x358637bd
	s_and_b64 vcc, exec, s[40:41]
	v_mov_b64_e32 v[26:27], s[54:55]
	v_mov_b64_e32 v[18:19], s[58:59]
	v_mov_b64_e32 v[22:23], s[50:51]
	v_mov_b64_e32 v[30:31], s[46:47]
	v_lshlrev_b32_e32 v214, 9, v53
	v_lshlrev_b32_e32 v40, 9, v54
	v_lshlrev_b32_e32 v38, 9, v55
	v_lshlrev_b32_e32 v36, 9, v56
	s_cbranch_vccnz .LBB0_521
; __device__ __forceinline__ f32x4 mfma16(bf16x8 a, bf16x8 b, f32x4 c) { return __builtin_amdgcn_mfma_f32_16x16x32_bf16(a, b, c, 0, 0, 0); }
; __device__ __forceinline__ void cmpsel_item(const Args& a, int it, unsigned char* lds, unsigned* cmp_done) {
;     ...
;             for (int half = 0; half < 2; ++half)
; #pragma unroll
;                 for (int kg = 0; kg < 2; ++kg) {
;                     if (2048 * kg + 31 > tmaxw) continue;
;                     bf16x8 vf[16];
; #pragma unroll
;                     for (int i = 0; i < 16; ++i) vf[i] = *(const bf16x8*)(Vc + (size_t)((half * 4 + (i & 3)) * 16 + fr) * 256 + (kg * 4 + (i >> 2)) * 32 + fq * 8);
; #pragma unroll
;                     for (int k4 = 0; k4 < 4; ++k4) {
;                         const bf16x8 av = *(const bf16x8*)(Pc + fr * 264 + (kg * 4 + k4) * 32 + fq * 8);
; #pragma unroll
;                         for (int dt = 0; dt < 4; ++dt) Oc[half * 4 + dt] = mfma16(av, vf[k4 * 4 + dt], Oc[half * 4 + dt]);
;                     }
;                 }
	v_mov_b32_e32 v39, v215
	v_lshl_add_u64 v[24:25], s[22:23], 0, v[38:39]
	v_lshl_add_u64 v[72:73], v[24:25], 0, v[34:35]
	global_load_dwordx4 v[120:123], v[72:73], off
	ds_read_b128 v[28:31], v45
	ds_read_b128 v[62:65], v45 offset:64
	v_lshl_add_u64 v[16:17], s[22:23], 0, v[214:215]
	v_lshl_add_u64 v[46:47], v[16:17], 0, v[34:35]
	global_load_dwordx4 v[124:127], v[46:47], off
	v_mov_b32_e32 v37, v215
	v_lshl_add_u64 v[58:59], s[22:23], 0, v[36:37]
	v_lshl_add_u64 v[74:75], v[58:59], 0, v[34:35]
	v_mov_b64_e32 v[60:61], s[50:51]
	v_mov_b64_e32 v[58:59], s[48:49]
	v_mov_b64_e32 v[56:57], s[54:55]
	v_mov_b64_e32 v[54:55], s[52:53]
	v_mov_b32_e32 v41, v215
	v_lshl_add_u64 v[20:21], s[22:23], 0, v[40:41]
	v_lshl_add_u64 v[70:71], v[20:21], 0, v[34:35]
	global_load_dwordx4 v[128:131], v[70:71], off
	v_mov_b64_e32 v[68:69], s[46:47]
	v_mov_b64_e32 v[66:67], s[44:45]
	global_load_dwordx4 v[132:135], v[46:47], off offset:64
	global_load_dwordx4 v[136:139], v[72:73], off offset:64
	global_load_dwordx4 v[140:143], v[46:47], off offset:128
	global_load_dwordx4 v[144:147], v[74:75], off
	global_load_dwordx4 v[148:151], v[70:71], off offset:64
	global_load_dwordx4 v[152:155], v[72:73], off offset:128
	global_load_dwordx4 v[156:159], v[46:47], off offset:192
	global_load_dwordx4 v[160:163], v[74:75], off offset:64
	global_load_dwordx4 v[164:167], v[70:71], off offset:128
	global_load_dwordx4 v[168:171], v[74:75], off offset:128
	global_load_dwordx4 v[172:175], v[70:71], off offset:192
	global_load_dwordx4 v[176:179], v[72:73], off offset:192
	global_load_dwordx4 v[180:183], v[74:75], off offset:192
	s_waitcnt lgkmcnt(1)
	s_waitcnt vmcnt(15)
	v_mfma_f32_16x16x32_bf16 v[24:27], v[28:31], v[120:123], v[58:61]
	s_nop 2
	s_nop 0
	s_nop 0
	s_waitcnt vmcnt(14)
	v_mfma_f32_16x16x32_bf16 v[16:19], v[28:31], v[124:127], v[54:57]
	s_nop 2
	v_mov_b64_e32 v[54:55], s[56:57]
	v_mov_b64_e32 v[56:57], s[58:59]
	s_waitcnt lgkmcnt(0)
	s_waitcnt vmcnt(12)
	v_mfma_f32_16x16x32_bf16 v[16:19], v[62:65], v[132:135], v[16:19]
	s_nop 0
	s_nop 0
	s_waitcnt vmcnt(11)
	v_mfma_f32_16x16x32_bf16 v[24:27], v[62:65], v[136:139], v[24:27]
	s_nop 0
	v_mfma_f32_16x16x32_bf16 v[20:23], v[28:31], v[128:131], v[54:57]
	s_nop 2
	s_nop 0
	s_nop 0
	s_waitcnt vmcnt(9)
	v_mfma_f32_16x16x32_bf16 v[28:31], v[28:31], v[144:147], v[66:69]
	s_nop 2
	ds_read_b128 v[66:69], v45 offset:128
	s_nop 0
	s_waitcnt lgkmcnt(0)
	v_mfma_f32_16x16x32_bf16 v[16:19], v[66:69], v[140:143], v[16:19]
	s_nop 0
	s_nop 0
	s_waitcnt vmcnt(7)
	v_mfma_f32_16x16x32_bf16 v[58:61], v[66:69], v[152:155], v[24:27]
	s_nop 2
	s_nop 0
	v_mfma_f32_16x16x32_bf16 v[20:23], v[62:65], v[148:151], v[20:23]
	s_nop 0
	s_nop 0
	s_waitcnt vmcnt(5)
	v_mfma_f32_16x16x32_bf16 v[28:31], v[62:65], v[160:163], v[28:31]
	s_nop 0
	s_nop 0
	s_waitcnt vmcnt(4)
	v_mfma_f32_16x16x32_bf16 v[20:23], v[66:69], v[164:167], v[20:23]
	s_nop 0
	s_nop 0
	s_waitcnt vmcnt(3)
	v_mfma_f32_16x16x32_bf16 v[28:31], v[66:69], v[168:171], v[28:31]
	ds_read_b128 v[54:57], v45 offset:192
	s_waitcnt lgkmcnt(0)
	v_mfma_f32_16x16x32_bf16 v[24:27], v[54:57], v[156:159], v[16:19]
	s_nop 2
	s_nop 0
	s_nop 0
	s_waitcnt vmcnt(2)
	v_mfma_f32_16x16x32_bf16 v[16:19], v[54:57], v[172:175], v[20:23]
	s_nop 2
	s_nop 0
	s_nop 0
	s_waitcnt vmcnt(1)
	v_mfma_f32_16x16x32_bf16 v[20:23], v[54:57], v[176:179], v[58:61]
	s_nop 2
	s_nop 0
	s_nop 0
	s_waitcnt vmcnt(0)
	v_mfma_f32_16x16x32_bf16 v[28:31], v[54:57], v[180:183], v[28:31]
.LBB0_521:
	s_and_b64 vcc, exec, s[42:43]
	s_cbranch_vccnz .LBB0_250
	v_mov_b32_e32 v41, v215
	v_mov_b32_e32 v39, v215
	v_lshl_add_u64 v[40:41], s[22:23], 0, v[40:41]
	v_lshl_add_u64 v[38:39], s[22:23], 0, v[38:39]
	v_lshl_add_u64 v[66:67], v[40:41], 0, v[34:35]
	v_lshl_add_u64 v[68:69], v[38:39], 0, v[34:35]
	global_load_dwordx4 v[120:123], v[66:67], off offset:256
	global_load_dwordx4 v[124:127], v[68:69], off offset:256
	v_lshl_add_u64 v[46:47], s[22:23], 0, v[214:215]
	v_lshl_add_u64 v[46:47], v[46:47], 0, v[34:35]
	global_load_dwordx4 v[128:131], v[46:47], off offset:256
	ds_read_b128 v[62:65], v45 offset:256
	v_mov_b32_e32 v37, v215
	v_lshl_add_u64 v[36:37], s[22:23], 0, v[36:37]
	v_lshl_add_u64 v[70:71], v[36:37], 0, v[34:35]
	global_load_dwordx4 v[132:135], v[70:71], off offset:256
	global_load_dwordx4 v[136:139], v[46:47], off offset:320
	global_load_dwordx4 v[140:143], v[68:69], off offset:320
	global_load_dwordx4 v[144:147], v[66:67], off offset:320
	global_load_dwordx4 v[148:151], v[46:47], off offset:384
	global_load_dwordx4 v[152:155], v[70:71], off offset:320
	global_load_dwordx4 v[156:159], v[68:69], off offset:384
	global_load_dwordx4 v[160:163], v[66:67], off offset:384
	global_load_dwordx4 v[164:167], v[46:47], off offset:448
	global_load_dwordx4 v[168:171], v[70:71], off offset:384
	global_load_dwordx4 v[172:175], v[66:67], off offset:448
	global_load_dwordx4 v[176:179], v[68:69], off offset:448
	global_load_dwordx4 v[180:183], v[70:71], off offset:448
	s_waitcnt lgkmcnt(0)
	s_waitcnt vmcnt(14)
	v_mfma_f32_16x16x32_bf16 v[20:23], v[62:65], v[124:127], v[20:23]
	s_nop 0
	s_nop 0
	s_waitcnt vmcnt(13)
	v_mfma_f32_16x16x32_bf16 v[24:27], v[62:65], v[128:131], v[24:27]
	ds_read_b128 v[54:57], v45 offset:320
	v_mfma_f32_16x16x32_bf16 v[16:19], v[62:65], v[120:123], v[16:19]
	ds_read_b128 v[58:61], v45 offset:384
	s_waitcnt lgkmcnt(1)
	s_waitcnt vmcnt(11)
	v_mfma_f32_16x16x32_bf16 v[24:27], v[54:57], v[136:139], v[24:27]
	s_nop 0
	v_mfma_f32_16x16x32_bf16 v[28:31], v[62:65], v[132:135], v[28:31]
	s_nop 0
	s_nop 0
	s_waitcnt vmcnt(10)
	v_mfma_f32_16x16x32_bf16 v[20:23], v[54:57], v[140:143], v[20:23]
	s_nop 0
	s_nop 0
	s_waitcnt vmcnt(9)
	v_mfma_f32_16x16x32_bf16 v[16:19], v[54:57], v[144:147], v[16:19]
	s_nop 0
	s_waitcnt lgkmcnt(0)
	s_waitcnt vmcnt(8)
	v_mfma_f32_16x16x32_bf16 v[24:27], v[58:61], v[148:151], v[24:27]
	s_nop 0
	s_nop 0
	s_waitcnt vmcnt(7)
	v_mfma_f32_16x16x32_bf16 v[28:31], v[54:57], v[152:155], v[28:31]
	s_nop 0
	s_nop 0
	s_waitcnt vmcnt(6)
	v_mfma_f32_16x16x32_bf16 v[20:23], v[58:61], v[156:159], v[20:23]
	s_nop 0
	s_nop 0
	s_waitcnt vmcnt(5)
	v_mfma_f32_16x16x32_bf16 v[16:19], v[58:61], v[160:163], v[16:19]
	s_nop 0
	s_nop 0
	s_waitcnt vmcnt(3)
	v_mfma_f32_16x16x32_bf16 v[28:31], v[58:61], v[168:171], v[28:31]
	ds_read_b128 v[34:37], v45 offset:448
	s_waitcnt lgkmcnt(0)
	v_mfma_f32_16x16x32_bf16 v[24:27], v[34:37], v[164:167], v[24:27]
	s_nop 0
	s_nop 0
	s_waitcnt vmcnt(2)
	v_mfma_f32_16x16x32_bf16 v[16:19], v[34:37], v[172:175], v[16:19]
	s_nop 0
	s_nop 0
	s_waitcnt vmcnt(1)
	v_mfma_f32_16x16x32_bf16 v[20:23], v[34:37], v[176:179], v[20:23]
	s_nop 0
	s_nop 0
	s_waitcnt vmcnt(0)
	v_mfma_f32_16x16x32_bf16 v[28:31], v[34:37], v[180:183], v[28:31]
	s_branch .LBB0_250

; #define TIDX opaque_tid()
; #define AIN(i) ((const float*)(__attribute__((address_space(1))) const float*)karg_u64(8 * (i)))
; #define WSP(T, off) ((T*)(__attribute__((address_space(1))) T*)(launder_ws(AWS, (off))))
; __device__ __forceinline__ void compress_item(const Args& a, int l, int it, unsigned char* lds, unsigned* cmp_done) {
;     const int which = it >> 6, bg = (it >> 4) & 3, rg = it & 15;
;     const int tid = TIDX, w = tid >> 6, lane = tid & 63, fr = lane & 15, fq = lane >> 4;
;     const float* X = WSP(const float, which ? WS_VCR : WS_KCR) + (size_t)bg * SEQ * 128;
;     const float* pe = sel_ptr(which != 0, AIN(9), AIN(8)) + (size_t)l * 32 * 128;
;     const bf16_t* W1t = WSP(const bf16_t, which ? WS_CV1 : WS_CK1);
;     const bf16_t* W2t = WSP(const bf16_t, which ? WS_CV2 : WS_CK2);
;     bf16_t* Hs = (bf16_t*)lds;
;     float* Part = (float*)(lds + 8192);
;     const int nc = rg * 16 + fr, ncl = nc < 255 ? nc : 254;
;     const float* arow = X + (size_t)ncl * 16 * 128 + w * 512 + fq * 8;
;     const bf16_t* brow = W1t + (size_t)fr * 4096 + w * 512 + fq * 8;
;     const float* per = pe + w * 512 + fq * 8;
;     f32x4 acc[8];
; #pragma unroll
;     for (int nt = 0; nt < 8; ++nt) acc[nt] = zero4();
;     __syncthreads();
; #pragma unroll 2
;     for (int kk = 0; kk < 16; ++kk) {
;         const f32x4 x0 = *(const f32x4*)(arow + kk * 32), x1 = *(const f32x4*)(arow + kk * 32 + 4);
;         const f32x4 p0 = *(const f32x4*)(per + kk * 32), p1 = *(const f32x4*)(per + kk * 32 + 4);
;         bf16x8 bfr[8];
; #pragma unroll
;         for (int nt = 0; nt < 8; ++nt) bfr[nt] = *(const bf16x8*)(brow + (size_t)nt * 16 * 4096 + kk * 32);
.LBB0_582:
	s_andn2_b64 vcc, exec, s[2:3]
	s_cbranch_vccnz .LBB0_221
	s_bfe_u32 s14, s13, 0x20004
	v_mov_b32_e32 v55, v224
	s_mov_b64 s[2:3], s[0:1]
	s_lshl_b32 s40, s14, 21
	s_load_dwordx2 s[22:23], s[2:3], 0xd0
	s_cmp_gt_u32 s13, 63
	s_mov_b32 s2, 0x1f018000
	s_cselect_b32 s92, s2, 0x1e818000
	s_mov_b64 s[24:25], s[92:93]
	s_mov_b64 s[2:3], s[0:1]
	s_mov_b64 s[20:21], s[0:1]
	s_load_dwordx2 s[2:3], s[2:3], 0x48
	s_load_dwordx2 s[20:21], s[20:21], 0x40
	s_waitcnt lgkmcnt(0)
	s_cselect_b32 s41, s3, s21
	s_cselect_b32 s42, s2, s20
	s_mov_b64 s[2:3], s[0:1]
	s_load_dwordx2 s[26:27], s[2:3], 0xd0
	s_mov_b32 s2, 0xab08000
	s_cselect_b32 s92, s2, 0xaa08000
	s_mov_b32 s15, 0xac10000
	s_mov_b64 s[38:39], s[92:93]
	s_cselect_b32 s92, s15, 0xac08000
	s_lshl_b32 s15, s13, 4
	v_and_b32_e32 v54, 15, v55
	s_and_b32 s15, s15, 0xf0
	s_waitcnt vmcnt(3)
	v_or_b32_e32 v0, s15, v54
	s_movk_i32 s43, 0xff
	v_ashrrev_i32_e32 v56, 6, v55
	v_lshlrev_b32_e32 v1, 11, v0
	v_cmp_ne_u32_e32 vcc, s43, v0
	v_mov_b32_e32 v0, 0x7f000
	v_lshlrev_b32_e32 v214, 13, v54
	s_waitcnt vmcnt(0)
	v_cndmask_b32_e32 v4, v0, v1, vcc
	v_lshlrev_b32_e32 v0, 9, v56
	v_lshl_add_u64 v[2:3], s[38:39], 0, v[214:215]
	v_and_b32_e32 v214, 48, v55
	v_ashrrev_i32_e32 v1, 31, v0
	v_lshl_add_u64 v[2:3], v[2:3], 0, v[214:215]
	s_mov_b64 s[2:3], s[0:1]
	v_lshl_add_u64 v[2:3], v[0:1], 1, v[2:3]
	v_lshlrev_b64 v[34:35], 2, v[0:1]
	s_add_u32 s24, s24, s40
	v_lshlrev_b32_e32 v0, 1, v55
	s_addc_u32 s25, s25, 0
	v_and_b32_e32 v214, 0x60, v0
	s_load_dwordx2 s[2:3], s[2:3], 0xd0
	s_waitcnt lgkmcnt(0)
	v_lshl_add_u64 v[32:33], s[26:27], 0, v[2:3]
	v_lshl_add_u64 v[0:1], s[24:25], 0, v[214:215]
	v_lshlrev_b32_e32 v2, 2, v4
	v_mov_b32_e32 v3, v215
	v_lshl_add_u64 v[0:1], v[0:1], 0, v[2:3]
	v_lshl_add_u64 v[36:37], s[22:23], 0, v[0:1]
	s_add_u32 s22, s42, s16
	s_mov_b64 s[20:21], s[92:93]
	s_mov_b32 s43, 0
	s_mov_b32 s44, 0
	s_mov_b32 s45, 0
	s_mov_b32 s46, 0
	s_mov_b32 s47, 0
	s_mov_b32 s48, 0
	s_mov_b32 s49, 0
	s_mov_b32 s50, s93
	s_addc_u32 s23, s41, s17
	v_lshrrev_b32_e32 v57, 4, v55
	v_lshl_add_u64 v[38:39], s[22:23], 0, v[214:215]
	s_mov_b64 s[22:23], 0
	v_mov_b32_e32 v0, s43
	v_mov_b32_e32 v8, s44
	v_mov_b32_e32 v4, s45
	v_mov_b32_e32 v20, s46
	v_mov_b32_e32 v12, s47
	v_mov_b32_e32 v24, s48
	v_mov_b32_e32 v16, s49
	v_mov_b32_e32 v28, s50
	v_mov_b32_e32 v1, s43
	v_mov_b32_e32 v2, s43
	v_mov_b32_e32 v3, s43
	v_mov_b32_e32 v9, s44
	v_mov_b32_e32 v10, s44
	v_mov_b32_e32 v11, s44
	v_mov_b32_e32 v5, s45
	v_mov_b32_e32 v6, s45
	v_mov_b32_e32 v7, s45
	v_mov_b32_e32 v21, s46
	v_mov_b32_e32 v22, s46
	v_mov_b32_e32 v23, s46
	v_mov_b32_e32 v13, s47
	v_mov_b32_e32 v14, s47
	v_mov_b32_e32 v15, s47
	v_mov_b32_e32 v25, s48
	v_mov_b32_e32 v26, s48
	v_mov_b32_e32 v27, s48
	v_mov_b32_e32 v17, s49
	v_mov_b32_e32 v18, s49
	v_mov_b32_e32 v19, s49
	v_mov_b32_e32 v29, s50
	v_mov_b32_e32 v30, s50
	v_mov_b32_e32 v31, s50
	s_barrier
	v_lshl_add_u64 v[40:41], v[36:37], 0, v[34:35]
	v_lshl_add_u64 v[42:43], v[38:39], 0, v[34:35]
	global_load_dwordx4 v[128:131], v[40:41], off
	global_load_dwordx4 v[132:135], v[40:41], off offset:16
	global_load_dwordx4 v[136:139], v[42:43], off
	global_load_dwordx4 v[140:143], v[42:43], off offset:16
	global_load_dwordx4 v[144:147], v[40:41], off offset:128
	global_load_dwordx4 v[148:151], v[40:41], off offset:144
	global_load_dwordx4 v[152:155], v[42:43], off offset:128
	global_load_dwordx4 v[156:159], v[42:43], off offset:144
	global_load_dwordx4 v[160:163], v[40:41], off offset:256
	global_load_dwordx4 v[164:167], v[40:41], off offset:272
	global_load_dwordx4 v[168:171], v[42:43], off offset:256
	global_load_dwordx4 v[172:175], v[42:43], off offset:272
	global_load_dwordx4 v[176:179], v[40:41], off offset:384
	global_load_dwordx4 v[180:183], v[40:41], off offset:400
	global_load_dwordx4 v[184:187], v[42:43], off offset:384
	global_load_dwordx4 v[188:191], v[42:43], off offset:400
	global_load_dwordx4 v[192:195], v[40:41], off offset:512
	global_load_dwordx4 v[196:199], v[40:41], off offset:528
	global_load_dwordx4 v[200:203], v[42:43], off offset:512
	global_load_dwordx4 v[204:207], v[42:43], off offset:528
	global_load_dwordx4 v[208:211], v[40:41], off offset:640
	global_load_dwordx4 v[216:219], v[40:41], off offset:656
	global_load_dwordx4 v[220:223], v[42:43], off offset:640
	global_load_dwordx4 v[238:241], v[42:43], off offset:656
	v_add_co_u32_e32 v44, vcc, 0x20000, v32
	s_nop 1
	v_addc_co_u32_e32 v45, vcc, 0, v33, vcc
	v_add_co_u32_e32 v46, vcc, 0x40000, v32
	s_nop 1
	v_addc_co_u32_e32 v47, vcc, 0, v33, vcc
	v_add_co_u32_e32 v48, vcc, 0x60000, v32
	s_nop 1
	v_addc_co_u32_e32 v49, vcc, 0, v33, vcc
	v_add_co_u32_e32 v50, vcc, 0x80000, v32
	s_nop 1
	v_addc_co_u32_e32 v51, vcc, 0, v33, vcc
	v_add_co_u32_e32 v52, vcc, 0xa0000, v32
	s_nop 1
	v_addc_co_u32_e32 v53, vcc, 0, v33, vcc
	v_add_co_u32_e32 v58, vcc, 0xc0000, v32
	s_nop 1
	v_addc_co_u32_e32 v59, vcc, 0, v33, vcc
	v_add_co_u32_e32 v60, vcc, 0xe0000, v32
	s_nop 1
	v_addc_co_u32_e32 v61, vcc, 0, v33, vcc
	s_waitcnt vmcnt(0)
; __device__ __forceinline__ void compress_item(const Args& a, int l, int it, unsigned char* lds, unsigned* cmp_done) {
;     ...
; #pragma unroll 2
;     for (int kk = 0; kk < 16; ++kk) {
;         const f32x4 x0 = *(const f32x4*)(arow + kk * 32), x1 = *(const f32x4*)(arow + kk * 32 + 4);
;         const f32x4 p0 = *(const f32x4*)(per + kk * 32), p1 = *(const f32x4*)(per + kk * 32 + 4);
;         bf16x8 bfr[8];
; #pragma unroll
;         for (int nt = 0; nt < 8; ++nt) bfr[nt] = *(const bf16x8*)(brow + (size_t)nt * 16 * 4096 + kk * 32);
;         const bf16x8 av = pack8(x0 + p0, x1 + p1);
	v_pk_add_f32 v[128:129], v[128:129], v[136:137]
	v_pk_add_f32 v[130:131], v[130:131], v[138:139]
	v_pk_add_f32 v[132:133], v[132:133], v[140:141]
	v_pk_add_f32 v[134:135], v[134:135], v[142:143]
	v_cvt_pk_bf16_f32 v64, v128, v129
	v_cvt_pk_bf16_f32 v65, v130, v131
	v_cvt_pk_bf16_f32 v66, v132, v133
	v_cvt_pk_bf16_f32 v67, v134, v135
	v_pk_add_f32 v[144:145], v[144:145], v[152:153]
	v_pk_add_f32 v[146:147], v[146:147], v[154:155]
	v_pk_add_f32 v[148:149], v[148:149], v[156:157]
	v_pk_add_f32 v[150:151], v[150:151], v[158:159]
	v_cvt_pk_bf16_f32 v68, v144, v145
	v_cvt_pk_bf16_f32 v69, v146, v147
	v_cvt_pk_bf16_f32 v70, v148, v149
	v_cvt_pk_bf16_f32 v71, v150, v151
	v_pk_add_f32 v[160:161], v[160:161], v[168:169]
	v_pk_add_f32 v[162:163], v[162:163], v[170:171]
	v_pk_add_f32 v[164:165], v[164:165], v[172:173]
	v_pk_add_f32 v[166:167], v[166:167], v[174:175]
	v_cvt_pk_bf16_f32 v72, v160, v161
	v_cvt_pk_bf16_f32 v73, v162, v163
	v_cvt_pk_bf16_f32 v74, v164, v165
	v_cvt_pk_bf16_f32 v75, v166, v167
	v_pk_add_f32 v[176:177], v[176:177], v[184:185]
	v_pk_add_f32 v[178:179], v[178:179], v[186:187]
	v_pk_add_f32 v[180:181], v[180:181], v[188:189]
	v_pk_add_f32 v[182:183], v[182:183], v[190:191]
	v_cvt_pk_bf16_f32 v76, v176, v177
	v_cvt_pk_bf16_f32 v77, v178, v179
	v_cvt_pk_bf16_f32 v78, v180, v181
	v_cvt_pk_bf16_f32 v79, v182, v183
	v_pk_add_f32 v[192:193], v[192:193], v[200:201]
	v_pk_add_f32 v[194:195], v[194:195], v[202:203]
	v_pk_add_f32 v[196:197], v[196:197], v[204:205]
	v_pk_add_f32 v[198:199], v[198:199], v[206:207]
	v_cvt_pk_bf16_f32 v80, v192, v193
	v_cvt_pk_bf16_f32 v81, v194, v195
	v_cvt_pk_bf16_f32 v82, v196, v197
	v_cvt_pk_bf16_f32 v83, v198, v199
	v_pk_add_f32 v[208:209], v[208:209], v[220:221]
	v_pk_add_f32 v[210:211], v[210:211], v[222:223]
	v_pk_add_f32 v[216:217], v[216:217], v[238:239]
	v_pk_add_f32 v[218:219], v[218:219], v[240:241]
	v_cvt_pk_bf16_f32 v84, v208, v209
	v_cvt_pk_bf16_f32 v85, v210, v211
	v_cvt_pk_bf16_f32 v86, v216, v217
	v_cvt_pk_bf16_f32 v87, v218, v219
	global_load_dwordx4 v[128:131], v[40:41], off offset:768
	global_load_dwordx4 v[132:135], v[40:41], off offset:784
	global_load_dwordx4 v[136:139], v[42:43], off offset:768
	global_load_dwordx4 v[140:143], v[42:43], off offset:784
	global_load_dwordx4 v[144:147], v[40:41], off offset:896
	global_load_dwordx4 v[148:151], v[40:41], off offset:912
	global_load_dwordx4 v[152:155], v[42:43], off offset:896
	global_load_dwordx4 v[156:159], v[42:43], off offset:912
	global_load_dwordx4 v[160:163], v[40:41], off offset:1024
	global_load_dwordx4 v[164:167], v[40:41], off offset:1040
	global_load_dwordx4 v[168:171], v[42:43], off offset:1024
	global_load_dwordx4 v[172:175], v[42:43], off offset:1040
	global_load_dwordx4 v[176:179], v[40:41], off offset:1152
	global_load_dwordx4 v[180:183], v[40:41], off offset:1168
	global_load_dwordx4 v[184:187], v[42:43], off offset:1152
	global_load_dwordx4 v[188:191], v[42:43], off offset:1168
	global_load_dwordx4 v[192:195], v[40:41], off offset:1280
	global_load_dwordx4 v[196:199], v[40:41], off offset:1296
	global_load_dwordx4 v[200:203], v[42:43], off offset:1280
	global_load_dwordx4 v[204:207], v[42:43], off offset:1296
	global_load_dwordx4 v[208:211], v[40:41], off offset:1408
	global_load_dwordx4 v[216:219], v[40:41], off offset:1424
	global_load_dwordx4 v[220:223], v[42:43], off offset:1408
	global_load_dwordx4 v[238:241], v[42:43], off offset:1424
	s_waitcnt vmcnt(0)
	v_pk_add_f32 v[128:129], v[128:129], v[136:137]
	v_pk_add_f32 v[130:131], v[130:131], v[138:139]
	v_pk_add_f32 v[132:133], v[132:133], v[140:141]
	v_pk_add_f32 v[134:135], v[134:135], v[142:143]
	v_cvt_pk_bf16_f32 v88, v128, v129
	v_cvt_pk_bf16_f32 v89, v130, v131
	v_cvt_pk_bf16_f32 v90, v132, v133
	v_cvt_pk_bf16_f32 v91, v134, v135
	v_pk_add_f32 v[144:145], v[144:145], v[152:153]
	v_pk_add_f32 v[146:147], v[146:147], v[154:155]
	v_pk_add_f32 v[148:149], v[148:149], v[156:157]
	v_pk_add_f32 v[150:151], v[150:151], v[158:159]
	v_cvt_pk_bf16_f32 v92, v144, v145
	v_cvt_pk_bf16_f32 v93, v146, v147
	v_cvt_pk_bf16_f32 v94, v148, v149
	v_cvt_pk_bf16_f32 v95, v150, v151
	v_pk_add_f32 v[160:161], v[160:161], v[168:169]
	v_pk_add_f32 v[162:163], v[162:163], v[170:171]
	v_pk_add_f32 v[164:165], v[164:165], v[172:173]
	v_pk_add_f32 v[166:167], v[166:167], v[174:175]
	v_cvt_pk_bf16_f32 v96, v160, v161
	v_cvt_pk_bf16_f32 v97, v162, v163
	v_cvt_pk_bf16_f32 v98, v164, v165
	v_cvt_pk_bf16_f32 v99, v166, v167
	v_pk_add_f32 v[176:177], v[176:177], v[184:185]
	v_pk_add_f32 v[178:179], v[178:179], v[186:187]
	v_pk_add_f32 v[180:181], v[180:181], v[188:189]
	v_pk_add_f32 v[182:183], v[182:183], v[190:191]
	v_cvt_pk_bf16_f32 v100, v176, v177
	v_cvt_pk_bf16_f32 v101, v178, v179
	v_cvt_pk_bf16_f32 v102, v180, v181
	v_cvt_pk_bf16_f32 v103, v182, v183
	v_pk_add_f32 v[192:193], v[192:193], v[200:201]
	v_pk_add_f32 v[194:195], v[194:195], v[202:203]
	v_pk_add_f32 v[196:197], v[196:197], v[204:205]
	v_pk_add_f32 v[198:199], v[198:199], v[206:207]
	v_cvt_pk_bf16_f32 v104, v192, v193
	v_cvt_pk_bf16_f32 v105, v194, v195
	v_cvt_pk_bf16_f32 v106, v196, v197
	v_cvt_pk_bf16_f32 v107, v198, v199
	v_pk_add_f32 v[208:209], v[208:209], v[220:221]
	v_pk_add_f32 v[210:211], v[210:211], v[222:223]
	v_pk_add_f32 v[216:217], v[216:217], v[238:239]
	v_pk_add_f32 v[218:219], v[218:219], v[240:241]
	v_cvt_pk_bf16_f32 v108, v208, v209
	v_cvt_pk_bf16_f32 v109, v210, v211
	v_cvt_pk_bf16_f32 v110, v216, v217
	v_cvt_pk_bf16_f32 v111, v218, v219
	global_load_dwordx4 v[128:131], v[40:41], off offset:1536
	global_load_dwordx4 v[132:135], v[40:41], off offset:1552
	global_load_dwordx4 v[136:139], v[42:43], off offset:1536
	global_load_dwordx4 v[140:143], v[42:43], off offset:1552
	global_load_dwordx4 v[144:147], v[40:41], off offset:1664
	global_load_dwordx4 v[148:151], v[40:41], off offset:1680
	global_load_dwordx4 v[152:155], v[42:43], off offset:1664
	global_load_dwordx4 v[156:159], v[42:43], off offset:1680
	global_load_dwordx4 v[160:163], v[40:41], off offset:1792
	global_load_dwordx4 v[164:167], v[40:41], off offset:1808
	global_load_dwordx4 v[168:171], v[42:43], off offset:1792
	global_load_dwordx4 v[172:175], v[42:43], off offset:1808
	global_load_dwordx4 v[176:179], v[40:41], off offset:1920
	global_load_dwordx4 v[180:183], v[40:41], off offset:1936
	global_load_dwordx4 v[184:187], v[42:43], off offset:1920
	global_load_dwordx4 v[188:191], v[42:43], off offset:1936
	global_load_dwordx4 v[192:195], v[32:33], off
	global_load_dwordx4 v[196:199], v[44:45], off
	global_load_dwordx4 v[200:203], v[46:47], off
	global_load_dwordx4 v[204:207], v[48:49], off
	global_load_dwordx4 v[208:211], v[50:51], off
	global_load_dwordx4 v[216:219], v[52:53], off
	global_load_dwordx4 v[220:223], v[58:59], off
	global_load_dwordx4 v[238:241], v[60:61], off
	s_waitcnt vmcnt(8)
; __device__ __forceinline__ f32x4 mfma16(bf16x8 a, bf16x8 b, f32x4 c) { return __builtin_amdgcn_mfma_f32_16x16x32_bf16(a, b, c, 0, 0, 0); }
; __device__ __forceinline__ void compress_item(const Args& a, int l, int it, unsigned char* lds, unsigned* cmp_done) {
;     ...
;         for (int nt = 0; nt < 8; ++nt) bfr[nt] = *(const bf16x8*)(brow + (size_t)nt * 16 * 4096 + kk * 32);
;         const bf16x8 av = pack8(x0 + p0, x1 + p1);
; #pragma unroll
;         for (int nt = 0; nt < 8; ++nt) acc[nt] = mfma16(av, bfr[nt], acc[nt]);
	v_pk_add_f32 v[128:129], v[128:129], v[136:137]
	v_pk_add_f32 v[130:131], v[130:131], v[138:139]
	v_pk_add_f32 v[132:133], v[132:133], v[140:141]
	v_pk_add_f32 v[134:135], v[134:135], v[142:143]
	v_cvt_pk_bf16_f32 v112, v128, v129
	v_cvt_pk_bf16_f32 v113, v130, v131
	v_cvt_pk_bf16_f32 v114, v132, v133
	v_cvt_pk_bf16_f32 v115, v134, v135
	v_pk_add_f32 v[144:145], v[144:145], v[152:153]
	v_pk_add_f32 v[146:147], v[146:147], v[154:155]
	v_pk_add_f32 v[148:149], v[148:149], v[156:157]
	v_pk_add_f32 v[150:151], v[150:151], v[158:159]
	v_cvt_pk_bf16_f32 v116, v144, v145
	v_cvt_pk_bf16_f32 v117, v146, v147
	v_cvt_pk_bf16_f32 v118, v148, v149
	v_cvt_pk_bf16_f32 v119, v150, v151
	v_pk_add_f32 v[160:161], v[160:161], v[168:169]
	v_pk_add_f32 v[162:163], v[162:163], v[170:171]
	v_pk_add_f32 v[164:165], v[164:165], v[172:173]
	v_pk_add_f32 v[166:167], v[166:167], v[174:175]
	v_cvt_pk_bf16_f32 v120, v160, v161
	v_cvt_pk_bf16_f32 v121, v162, v163
	v_cvt_pk_bf16_f32 v122, v164, v165
	v_cvt_pk_bf16_f32 v123, v166, v167
	v_pk_add_f32 v[176:177], v[176:177], v[184:185]
	v_pk_add_f32 v[178:179], v[178:179], v[186:187]
	v_pk_add_f32 v[180:181], v[180:181], v[188:189]
	v_pk_add_f32 v[182:183], v[182:183], v[190:191]
	v_cvt_pk_bf16_f32 v124, v176, v177
	v_cvt_pk_bf16_f32 v125, v178, v179
	v_cvt_pk_bf16_f32 v126, v180, v181
	v_cvt_pk_bf16_f32 v127, v182, v183
	global_load_dwordx4 v[128:131], v[32:33], off offset:64
	global_load_dwordx4 v[132:135], v[44:45], off offset:64
	global_load_dwordx4 v[136:139], v[46:47], off offset:64
	global_load_dwordx4 v[140:143], v[48:49], off offset:64
	global_load_dwordx4 v[144:147], v[50:51], off offset:64
	global_load_dwordx4 v[148:151], v[52:53], off offset:64
	global_load_dwordx4 v[152:155], v[58:59], off offset:64
	global_load_dwordx4 v[156:159], v[60:61], off offset:64
	global_load_dwordx4 v[160:163], v[32:33], off offset:128
	global_load_dwordx4 v[164:167], v[44:45], off offset:128
	global_load_dwordx4 v[168:171], v[46:47], off offset:128
	global_load_dwordx4 v[172:175], v[48:49], off offset:128
	global_load_dwordx4 v[176:179], v[50:51], off offset:128
	global_load_dwordx4 v[180:183], v[52:53], off offset:128
	global_load_dwordx4 v[184:187], v[58:59], off offset:128
	global_load_dwordx4 v[188:191], v[60:61], off offset:128
	s_waitcnt vmcnt(16)
	v_mfma_f32_16x16x32_bf16 v[0:3], v[64:67], v[192:195], v[0:3]
	v_mfma_f32_16x16x32_bf16 v[8:11], v[64:67], v[196:199], v[8:11]
	v_mfma_f32_16x16x32_bf16 v[4:7], v[64:67], v[200:203], v[4:7]
	v_mfma_f32_16x16x32_bf16 v[20:23], v[64:67], v[204:207], v[20:23]
	v_mfma_f32_16x16x32_bf16 v[12:15], v[64:67], v[208:211], v[12:15]
	v_mfma_f32_16x16x32_bf16 v[24:27], v[64:67], v[216:219], v[24:27]
	v_mfma_f32_16x16x32_bf16 v[16:19], v[64:67], v[220:223], v[16:19]
	v_mfma_f32_16x16x32_bf16 v[28:31], v[64:67], v[238:241], v[28:31]
	global_load_dwordx4 v[192:195], v[32:33], off offset:192
	global_load_dwordx4 v[196:199], v[44:45], off offset:192
	global_load_dwordx4 v[200:203], v[46:47], off offset:192
	global_load_dwordx4 v[204:207], v[48:49], off offset:192
	global_load_dwordx4 v[208:211], v[50:51], off offset:192
	global_load_dwordx4 v[216:219], v[52:53], off offset:192
	global_load_dwordx4 v[220:223], v[58:59], off offset:192
	global_load_dwordx4 v[238:241], v[60:61], off offset:192
	s_waitcnt vmcnt(16)
	v_mfma_f32_16x16x32_bf16 v[0:3], v[68:71], v[128:131], v[0:3]
	v_mfma_f32_16x16x32_bf16 v[8:11], v[68:71], v[132:135], v[8:11]
	v_mfma_f32_16x16x32_bf16 v[4:7], v[68:71], v[136:139], v[4:7]
	v_mfma_f32_16x16x32_bf16 v[20:23], v[68:71], v[140:143], v[20:23]
	v_mfma_f32_16x16x32_bf16 v[12:15], v[68:71], v[144:147], v[12:15]
	v_mfma_f32_16x16x32_bf16 v[24:27], v[68:71], v[148:151], v[24:27]
	v_mfma_f32_16x16x32_bf16 v[16:19], v[68:71], v[152:155], v[16:19]
	v_mfma_f32_16x16x32_bf16 v[28:31], v[68:71], v[156:159], v[28:31]
	global_load_dwordx4 v[128:131], v[32:33], off offset:256
	global_load_dwordx4 v[132:135], v[44:45], off offset:256
	global_load_dwordx4 v[136:139], v[46:47], off offset:256
	global_load_dwordx4 v[140:143], v[48:49], off offset:256
	global_load_dwordx4 v[144:147], v[50:51], off offset:256
	global_load_dwordx4 v[148:151], v[52:53], off offset:256
	global_load_dwordx4 v[152:155], v[58:59], off offset:256
	global_load_dwordx4 v[156:159], v[60:61], off offset:256
	s_waitcnt vmcnt(16)
	v_mfma_f32_16x16x32_bf16 v[0:3], v[72:75], v[160:163], v[0:3]
	v_mfma_f32_16x16x32_bf16 v[8:11], v[72:75], v[164:167], v[8:11]
	v_mfma_f32_16x16x32_bf16 v[4:7], v[72:75], v[168:171], v[4:7]
	v_mfma_f32_16x16x32_bf16 v[20:23], v[72:75], v[172:175], v[20:23]
	v_mfma_f32_16x16x32_bf16 v[12:15], v[72:75], v[176:179], v[12:15]
	v_mfma_f32_16x16x32_bf16 v[24:27], v[72:75], v[180:183], v[24:27]
	v_mfma_f32_16x16x32_bf16 v[16:19], v[72:75], v[184:187], v[16:19]
	v_mfma_f32_16x16x32_bf16 v[28:31], v[72:75], v[188:191], v[28:31]
	global_load_dwordx4 v[160:163], v[32:33], off offset:320
	global_load_dwordx4 v[164:167], v[44:45], off offset:320
	global_load_dwordx4 v[168:171], v[46:47], off offset:320
	global_load_dwordx4 v[172:175], v[48:49], off offset:320
	global_load_dwordx4 v[176:179], v[50:51], off offset:320
	global_load_dwordx4 v[180:183], v[52:53], off offset:320
	global_load_dwordx4 v[184:187], v[58:59], off offset:320
	global_load_dwordx4 v[188:191], v[60:61], off offset:320
	s_waitcnt vmcnt(16)
; __device__ __forceinline__ f32x4 mfma16(bf16x8 a, bf16x8 b, f32x4 c) { return __builtin_amdgcn_mfma_f32_16x16x32_bf16(a, b, c, 0, 0, 0); }
; __device__ __forceinline__ void compress_item(const Args& a, int l, int it, unsigned char* lds, unsigned* cmp_done) {
;     ...
;         for (int nt = 0; nt < 8; ++nt) bfr[nt] = *(const bf16x8*)(brow + (size_t)nt * 16 * 4096 + kk * 32);
;         const bf16x8 av = pack8(x0 + p0, x1 + p1);
; #pragma unroll
;         for (int nt = 0; nt < 8; ++nt) acc[nt] = mfma16(av, bfr[nt], acc[nt]);
	v_mfma_f32_16x16x32_bf16 v[0:3], v[76:79], v[192:195], v[0:3]
	v_mfma_f32_16x16x32_bf16 v[8:11], v[76:79], v[196:199], v[8:11]
	v_mfma_f32_16x16x32_bf16 v[4:7], v[76:79], v[200:203], v[4:7]
	v_mfma_f32_16x16x32_bf16 v[20:23], v[76:79], v[204:207], v[20:23]
	v_mfma_f32_16x16x32_bf16 v[12:15], v[76:79], v[208:211], v[12:15]
	v_mfma_f32_16x16x32_bf16 v[24:27], v[76:79], v[216:219], v[24:27]
	v_mfma_f32_16x16x32_bf16 v[16:19], v[76:79], v[220:223], v[16:19]
	v_mfma_f32_16x16x32_bf16 v[28:31], v[76:79], v[238:241], v[28:31]
	global_load_dwordx4 v[192:195], v[32:33], off offset:384
	global_load_dwordx4 v[196:199], v[44:45], off offset:384
	global_load_dwordx4 v[200:203], v[46:47], off offset:384
	global_load_dwordx4 v[204:207], v[48:49], off offset:384
	global_load_dwordx4 v[208:211], v[50:51], off offset:384
	global_load_dwordx4 v[216:219], v[52:53], off offset:384
	global_load_dwordx4 v[220:223], v[58:59], off offset:384
	global_load_dwordx4 v[238:241], v[60:61], off offset:384
	s_waitcnt vmcnt(16)
	v_mfma_f32_16x16x32_bf16 v[0:3], v[80:83], v[128:131], v[0:3]
	v_mfma_f32_16x16x32_bf16 v[8:11], v[80:83], v[132:135], v[8:11]
	v_mfma_f32_16x16x32_bf16 v[4:7], v[80:83], v[136:139], v[4:7]
	v_mfma_f32_16x16x32_bf16 v[20:23], v[80:83], v[140:143], v[20:23]
	v_mfma_f32_16x16x32_bf16 v[12:15], v[80:83], v[144:147], v[12:15]
	v_mfma_f32_16x16x32_bf16 v[24:27], v[80:83], v[148:151], v[24:27]
	v_mfma_f32_16x16x32_bf16 v[16:19], v[80:83], v[152:155], v[16:19]
	v_mfma_f32_16x16x32_bf16 v[28:31], v[80:83], v[156:159], v[28:31]
	global_load_dwordx4 v[128:131], v[32:33], off offset:448
	global_load_dwordx4 v[132:135], v[44:45], off offset:448
	global_load_dwordx4 v[136:139], v[46:47], off offset:448
	global_load_dwordx4 v[140:143], v[48:49], off offset:448
	global_load_dwordx4 v[144:147], v[50:51], off offset:448
	global_load_dwordx4 v[148:151], v[52:53], off offset:448
	global_load_dwordx4 v[152:155], v[58:59], off offset:448
	global_load_dwordx4 v[156:159], v[60:61], off offset:448
	s_waitcnt vmcnt(16)
	v_mfma_f32_16x16x32_bf16 v[0:3], v[84:87], v[160:163], v[0:3]
	v_mfma_f32_16x16x32_bf16 v[8:11], v[84:87], v[164:167], v[8:11]
	v_mfma_f32_16x16x32_bf16 v[4:7], v[84:87], v[168:171], v[4:7]
	v_mfma_f32_16x16x32_bf16 v[20:23], v[84:87], v[172:175], v[20:23]
	v_mfma_f32_16x16x32_bf16 v[12:15], v[84:87], v[176:179], v[12:15]
	v_mfma_f32_16x16x32_bf16 v[24:27], v[84:87], v[180:183], v[24:27]
	v_mfma_f32_16x16x32_bf16 v[16:19], v[84:87], v[184:187], v[16:19]
	v_mfma_f32_16x16x32_bf16 v[28:31], v[84:87], v[188:191], v[28:31]
	global_load_dwordx4 v[160:163], v[32:33], off offset:512
	global_load_dwordx4 v[164:167], v[44:45], off offset:512
	global_load_dwordx4 v[168:171], v[46:47], off offset:512
	global_load_dwordx4 v[172:175], v[48:49], off offset:512
	global_load_dwordx4 v[176:179], v[50:51], off offset:512
	global_load_dwordx4 v[180:183], v[52:53], off offset:512
	global_load_dwordx4 v[184:187], v[58:59], off offset:512
	global_load_dwordx4 v[188:191], v[60:61], off offset:512
	s_waitcnt vmcnt(16)
	v_mfma_f32_16x16x32_bf16 v[0:3], v[88:91], v[192:195], v[0:3]
	v_mfma_f32_16x16x32_bf16 v[8:11], v[88:91], v[196:199], v[8:11]
	v_mfma_f32_16x16x32_bf16 v[4:7], v[88:91], v[200:203], v[4:7]
	v_mfma_f32_16x16x32_bf16 v[20:23], v[88:91], v[204:207], v[20:23]
	v_mfma_f32_16x16x32_bf16 v[12:15], v[88:91], v[208:211], v[12:15]
	v_mfma_f32_16x16x32_bf16 v[24:27], v[88:91], v[216:219], v[24:27]
	v_mfma_f32_16x16x32_bf16 v[16:19], v[88:91], v[220:223], v[16:19]
	v_mfma_f32_16x16x32_bf16 v[28:31], v[88:91], v[238:241], v[28:31]
	global_load_dwordx4 v[192:195], v[32:33], off offset:576
	global_load_dwordx4 v[196:199], v[44:45], off offset:576
	global_load_dwordx4 v[200:203], v[46:47], off offset:576
	global_load_dwordx4 v[204:207], v[48:49], off offset:576
	global_load_dwordx4 v[208:211], v[50:51], off offset:576
	global_load_dwordx4 v[216:219], v[52:53], off offset:576
	global_load_dwordx4 v[220:223], v[58:59], off offset:576
	global_load_dwordx4 v[238:241], v[60:61], off offset:576
	s_waitcnt vmcnt(16)
	v_mfma_f32_16x16x32_bf16 v[0:3], v[92:95], v[128:131], v[0:3]
	v_mfma_f32_16x16x32_bf16 v[8:11], v[92:95], v[132:135], v[8:11]
	v_mfma_f32_16x16x32_bf16 v[4:7], v[92:95], v[136:139], v[4:7]
	v_mfma_f32_16x16x32_bf16 v[20:23], v[92:95], v[140:143], v[20:23]
	v_mfma_f32_16x16x32_bf16 v[12:15], v[92:95], v[144:147], v[12:15]
	v_mfma_f32_16x16x32_bf16 v[24:27], v[92:95], v[148:151], v[24:27]
	v_mfma_f32_16x16x32_bf16 v[16:19], v[92:95], v[152:155], v[16:19]
	v_mfma_f32_16x16x32_bf16 v[28:31], v[92:95], v[156:159], v[28:31]
	global_load_dwordx4 v[128:131], v[32:33], off offset:640
	global_load_dwordx4 v[132:135], v[44:45], off offset:640
	global_load_dwordx4 v[136:139], v[46:47], off offset:640
	global_load_dwordx4 v[140:143], v[48:49], off offset:640
	global_load_dwordx4 v[144:147], v[50:51], off offset:640
	global_load_dwordx4 v[148:151], v[52:53], off offset:640
	global_load_dwordx4 v[152:155], v[58:59], off offset:640
	global_load_dwordx4 v[156:159], v[60:61], off offset:640
	s_waitcnt vmcnt(16)
	v_mfma_f32_16x16x32_bf16 v[0:3], v[96:99], v[160:163], v[0:3]
	v_mfma_f32_16x16x32_bf16 v[8:11], v[96:99], v[164:167], v[8:11]
	v_mfma_f32_16x16x32_bf16 v[4:7], v[96:99], v[168:171], v[4:7]
	v_mfma_f32_16x16x32_bf16 v[20:23], v[96:99], v[172:175], v[20:23]
	v_mfma_f32_16x16x32_bf16 v[12:15], v[96:99], v[176:179], v[12:15]
	v_mfma_f32_16x16x32_bf16 v[24:27], v[96:99], v[180:183], v[24:27]
	v_mfma_f32_16x16x32_bf16 v[16:19], v[96:99], v[184:187], v[16:19]
	v_mfma_f32_16x16x32_bf16 v[28:31], v[96:99], v[188:191], v[28:31]
	global_load_dwordx4 v[160:163], v[32:33], off offset:704
	global_load_dwordx4 v[164:167], v[44:45], off offset:704
	global_load_dwordx4 v[168:171], v[46:47], off offset:704
	global_load_dwordx4 v[172:175], v[48:49], off offset:704
	global_load_dwordx4 v[176:179], v[50:51], off offset:704
	global_load_dwordx4 v[180:183], v[52:53], off offset:704
	global_load_dwordx4 v[184:187], v[58:59], off offset:704
	global_load_dwordx4 v[188:191], v[60:61], off offset:704
	s_waitcnt vmcnt(16)
; __device__ __forceinline__ f32x4 mfma16(bf16x8 a, bf16x8 b, f32x4 c) { return __builtin_amdgcn_mfma_f32_16x16x32_bf16(a, b, c, 0, 0, 0); }
; __device__ __forceinline__ void compress_item(const Args& a, int l, int it, unsigned char* lds, unsigned* cmp_done) {
;     ...
;         for (int nt = 0; nt < 8; ++nt) bfr[nt] = *(const bf16x8*)(brow + (size_t)nt * 16 * 4096 + kk * 32);
;         const bf16x8 av = pack8(x0 + p0, x1 + p1);
; #pragma unroll
;         for (int nt = 0; nt < 8; ++nt) acc[nt] = mfma16(av, bfr[nt], acc[nt]);
	v_mfma_f32_16x16x32_bf16 v[0:3], v[100:103], v[192:195], v[0:3]
	v_mfma_f32_16x16x32_bf16 v[8:11], v[100:103], v[196:199], v[8:11]
	v_mfma_f32_16x16x32_bf16 v[4:7], v[100:103], v[200:203], v[4:7]
	v_mfma_f32_16x16x32_bf16 v[20:23], v[100:103], v[204:207], v[20:23]
	v_mfma_f32_16x16x32_bf16 v[12:15], v[100:103], v[208:211], v[12:15]
	v_mfma_f32_16x16x32_bf16 v[24:27], v[100:103], v[216:219], v[24:27]
	v_mfma_f32_16x16x32_bf16 v[16:19], v[100:103], v[220:223], v[16:19]
	v_mfma_f32_16x16x32_bf16 v[28:31], v[100:103], v[238:241], v[28:31]
	global_load_dwordx4 v[192:195], v[32:33], off offset:768
	global_load_dwordx4 v[196:199], v[44:45], off offset:768
	global_load_dwordx4 v[200:203], v[46:47], off offset:768
	global_load_dwordx4 v[204:207], v[48:49], off offset:768
	global_load_dwordx4 v[208:211], v[50:51], off offset:768
	global_load_dwordx4 v[216:219], v[52:53], off offset:768
	global_load_dwordx4 v[220:223], v[58:59], off offset:768
	global_load_dwordx4 v[238:241], v[60:61], off offset:768
	s_waitcnt vmcnt(16)
	v_mfma_f32_16x16x32_bf16 v[0:3], v[104:107], v[128:131], v[0:3]
	v_mfma_f32_16x16x32_bf16 v[8:11], v[104:107], v[132:135], v[8:11]
	v_mfma_f32_16x16x32_bf16 v[4:7], v[104:107], v[136:139], v[4:7]
	v_mfma_f32_16x16x32_bf16 v[20:23], v[104:107], v[140:143], v[20:23]
	v_mfma_f32_16x16x32_bf16 v[12:15], v[104:107], v[144:147], v[12:15]
	v_mfma_f32_16x16x32_bf16 v[24:27], v[104:107], v[148:151], v[24:27]
	v_mfma_f32_16x16x32_bf16 v[16:19], v[104:107], v[152:155], v[16:19]
	v_mfma_f32_16x16x32_bf16 v[28:31], v[104:107], v[156:159], v[28:31]
	global_load_dwordx4 v[128:131], v[32:33], off offset:832
	global_load_dwordx4 v[132:135], v[44:45], off offset:832
	global_load_dwordx4 v[136:139], v[46:47], off offset:832
	global_load_dwordx4 v[140:143], v[48:49], off offset:832
	global_load_dwordx4 v[144:147], v[50:51], off offset:832
	global_load_dwordx4 v[148:151], v[52:53], off offset:832
	global_load_dwordx4 v[152:155], v[58:59], off offset:832
	global_load_dwordx4 v[156:159], v[60:61], off offset:832
	s_waitcnt vmcnt(16)
	v_mfma_f32_16x16x32_bf16 v[0:3], v[108:111], v[160:163], v[0:3]
	v_mfma_f32_16x16x32_bf16 v[8:11], v[108:111], v[164:167], v[8:11]
	v_mfma_f32_16x16x32_bf16 v[4:7], v[108:111], v[168:171], v[4:7]
	v_mfma_f32_16x16x32_bf16 v[20:23], v[108:111], v[172:175], v[20:23]
	v_mfma_f32_16x16x32_bf16 v[12:15], v[108:111], v[176:179], v[12:15]
	v_mfma_f32_16x16x32_bf16 v[24:27], v[108:111], v[180:183], v[24:27]
	v_mfma_f32_16x16x32_bf16 v[16:19], v[108:111], v[184:187], v[16:19]
	v_mfma_f32_16x16x32_bf16 v[28:31], v[108:111], v[188:191], v[28:31]
	global_load_dwordx4 v[160:163], v[32:33], off offset:896
	global_load_dwordx4 v[164:167], v[44:45], off offset:896
	global_load_dwordx4 v[168:171], v[46:47], off offset:896
	global_load_dwordx4 v[172:175], v[48:49], off offset:896
	global_load_dwordx4 v[176:179], v[50:51], off offset:896
	global_load_dwordx4 v[180:183], v[52:53], off offset:896
	global_load_dwordx4 v[184:187], v[58:59], off offset:896
	global_load_dwordx4 v[188:191], v[60:61], off offset:896
	s_waitcnt vmcnt(16)
	v_mfma_f32_16x16x32_bf16 v[0:3], v[112:115], v[192:195], v[0:3]
	v_mfma_f32_16x16x32_bf16 v[8:11], v[112:115], v[196:199], v[8:11]
	v_mfma_f32_16x16x32_bf16 v[4:7], v[112:115], v[200:203], v[4:7]
	v_mfma_f32_16x16x32_bf16 v[20:23], v[112:115], v[204:207], v[20:23]
	v_mfma_f32_16x16x32_bf16 v[12:15], v[112:115], v[208:211], v[12:15]
	v_mfma_f32_16x16x32_bf16 v[24:27], v[112:115], v[216:219], v[24:27]
	v_mfma_f32_16x16x32_bf16 v[16:19], v[112:115], v[220:223], v[16:19]
	v_mfma_f32_16x16x32_bf16 v[28:31], v[112:115], v[238:241], v[28:31]
	global_load_dwordx4 v[192:195], v[32:33], off offset:960
	global_load_dwordx4 v[196:199], v[44:45], off offset:960
	global_load_dwordx4 v[200:203], v[46:47], off offset:960
	global_load_dwordx4 v[204:207], v[48:49], off offset:960
	global_load_dwordx4 v[208:211], v[50:51], off offset:960
	global_load_dwordx4 v[216:219], v[52:53], off offset:960
	global_load_dwordx4 v[220:223], v[58:59], off offset:960
	global_load_dwordx4 v[238:241], v[60:61], off offset:960
	s_waitcnt vmcnt(16)
	v_mfma_f32_16x16x32_bf16 v[0:3], v[116:119], v[128:131], v[0:3]
	v_mfma_f32_16x16x32_bf16 v[8:11], v[116:119], v[132:135], v[8:11]
	v_mfma_f32_16x16x32_bf16 v[4:7], v[116:119], v[136:139], v[4:7]
	v_mfma_f32_16x16x32_bf16 v[20:23], v[116:119], v[140:143], v[20:23]
	v_mfma_f32_16x16x32_bf16 v[12:15], v[116:119], v[144:147], v[12:15]
	v_mfma_f32_16x16x32_bf16 v[24:27], v[116:119], v[148:151], v[24:27]
	v_mfma_f32_16x16x32_bf16 v[16:19], v[116:119], v[152:155], v[16:19]
	v_mfma_f32_16x16x32_bf16 v[28:31], v[116:119], v[156:159], v[28:31]
	s_waitcnt vmcnt(8)
	v_mfma_f32_16x16x32_bf16 v[0:3], v[120:123], v[160:163], v[0:3]
	v_mfma_f32_16x16x32_bf16 v[8:11], v[120:123], v[164:167], v[8:11]
	v_mfma_f32_16x16x32_bf16 v[4:7], v[120:123], v[168:171], v[4:7]
	v_mfma_f32_16x16x32_bf16 v[20:23], v[120:123], v[172:175], v[20:23]
	v_mfma_f32_16x16x32_bf16 v[12:15], v[120:123], v[176:179], v[12:15]
	v_mfma_f32_16x16x32_bf16 v[24:27], v[120:123], v[180:183], v[24:27]
	v_mfma_f32_16x16x32_bf16 v[16:19], v[120:123], v[184:187], v[16:19]
	v_mfma_f32_16x16x32_bf16 v[28:31], v[120:123], v[188:191], v[28:31]
	s_waitcnt vmcnt(0)
; __device__ __forceinline__ f32x4 mfma16(bf16x8 a, bf16x8 b, f32x4 c) { return __builtin_amdgcn_mfma_f32_16x16x32_bf16(a, b, c, 0, 0, 0); }
; __device__ __forceinline__ void compress_item(const Args& a, int l, int it, unsigned char* lds, unsigned* cmp_done) {
;     ...
;         for (int nt = 0; nt < 8; ++nt) bfr[nt] = *(const bf16x8*)(brow + (size_t)nt * 16 * 4096 + kk * 32);
;         const bf16x8 av = pack8(x0 + p0, x1 + p1);
; #pragma unroll
;         for (int nt = 0; nt < 8; ++nt) acc[nt] = mfma16(av, bfr[nt], acc[nt]);
;     }
; #pragma unroll
;     for (int nt = 0; nt < 8; ++nt)
; #pragma unroll
;         for (int j = 0; j < 4; ++j) Part[(w * 16 + fq * 4 + j) * 132 + nt * 16 + fr] = acc[nt][j];
;     __syncthreads();
;     {
;         const int row = tid >> 5, c4 = (tid & 31) * 4;
;         f32x4 sum = *(const f32x4*)(Part + row * 132 + c4);
	v_mfma_f32_16x16x32_bf16 v[0:3], v[124:127], v[192:195], v[0:3]
	v_mfma_f32_16x16x32_bf16 v[8:11], v[124:127], v[196:199], v[8:11]
	v_mfma_f32_16x16x32_bf16 v[4:7], v[124:127], v[200:203], v[4:7]
	v_mfma_f32_16x16x32_bf16 v[20:23], v[124:127], v[204:207], v[20:23]
	v_mfma_f32_16x16x32_bf16 v[12:15], v[124:127], v[208:211], v[12:15]
	v_mfma_f32_16x16x32_bf16 v[24:27], v[124:127], v[216:219], v[24:27]
	v_mfma_f32_16x16x32_bf16 v[16:19], v[124:127], v[220:223], v[16:19]
	v_mfma_f32_16x16x32_bf16 v[28:31], v[124:127], v[238:241], v[28:31]
	v_and_b32_e32 v33, 3, v57
	v_lshlrev_b32_e32 v34, 4, v56
	v_lshlrev_b32_e32 v32, 2, v33
	v_or_b32_e32 v35, v32, v34
	s_movk_i32 s22, 0x210
	v_lshlrev_b32_e32 v36, 2, v54
	v_mul_lo_u32 v35, v35, s22
	v_add3_u32 v35, 0, v36, v35
	v_add_u32_e32 v36, 0x2000, v35
	ds_write2_b32 v36, v0, v8 offset1:16
	ds_write2_b32 v36, v1, v9 offset0:132 offset1:148
	v_add_u32_e32 v0, 0x2400, v35
	ds_write2_b32 v0, v2, v10 offset0:8 offset1:24
	ds_write2_b32 v0, v3, v11 offset0:140 offset1:156
	ds_write2_b32 v36, v4, v20 offset0:32 offset1:48
	ds_write2_b32 v36, v5, v21 offset0:164 offset1:180
	ds_write2_b32 v0, v6, v22 offset0:40 offset1:56
	ds_write2_b32 v0, v7, v23 offset0:172 offset1:188
	ds_write2_b32 v36, v12, v24 offset0:64 offset1:80
	ds_write2_b32 v36, v13, v25 offset0:196 offset1:212
	ds_write2_b32 v0, v14, v26 offset0:72 offset1:88
	ds_write2_b32 v0, v15, v27 offset0:204 offset1:220
	ds_write2_b32 v36, v16, v28 offset0:96 offset1:112
	ds_write2_b32 v36, v17, v29 offset0:228 offset1:244
	ds_write2_b32 v0, v18, v30 offset0:104 offset1:120
	ds_write2_b32 v0, v19, v31 offset0:236 offset1:252
	v_ashrrev_i32_e32 v10, 5, v55
	v_lshlrev_b32_e32 v0, 2, v55
	v_and_b32_e32 v11, 0x7c, v0
	v_mul_lo_u32 v4, v10, s22
	v_add_u32_e32 v12, 0, v4
	v_lshlrev_b32_e32 v5, 2, v11
	v_add_u32_e32 v0, v12, v5
	v_add3_u32 v13, 0, v5, v4
	s_waitcnt lgkmcnt(0)
	s_barrier
; __device__ __forceinline__ unsigned pk2(float lo, float hi) { f32x2_t v = {lo, hi}; bf16x2_t b = __builtin_convertvector(v, bf16x2_t); return __builtin_bit_cast(unsigned, b); }
; __device__ __forceinline__ f32x4 mfma16(bf16x8 a, bf16x8 b, f32x4 c) { return __builtin_amdgcn_mfma_f32_16x16x32_bf16(a, b, c, 0, 0, 0); }
; #define WSP(T, off) ((T*)(__attribute__((address_space(1))) T*)(launder_ws(AWS, (off))))
; __device__ __forceinline__ void compress_item(const Args& a, int l, int it, unsigned char* lds, unsigned* cmp_done) {
;     ...
;     {
;         const int row = tid >> 5, c4 = (tid & 31) * 4;
;         f32x4 sum = *(const f32x4*)(Part + row * 132 + c4);
; #pragma unroll
;         for (int ww = 1; ww < 8; ++ww) sum = sum + *(const f32x4*)(Part + (ww * 16 + row) * 132 + c4);
;         u32x2 o; o.x = pk2(gelu_tanh(sum.x), gelu_tanh(sum.y)); o.y = pk2(gelu_tanh(sum.z), gelu_tanh(sum.w));
;         *(u32x2*)(Hs + row * 136 + c4) = o;
;     }
;     __syncthreads();
;     f32x4 acc2 = zero4();
; #pragma unroll
;     for (int ks = 0; ks < 4; ++ks)
;         acc2 = mfma16(*(const bf16x8*)(Hs + fr * 136 + ks * 32 + fq * 8), *(const bf16x8*)(W2t + (size_t)(w * 16 + fr) * 128 + ks * 32 + fq * 8), acc2);
;     const int dcol = w * 16 + fr;
;     if (which == 0) {
; #pragma unroll
;         for (int j = 0; j < 4; ++j) { const int r = rg * 16 + fq * 4 + j; WSP(bf16_t, WS_KCB)[((size_t)bg * 256 + r) * 128 + dcol] = r < 255 ? f2bf(acc2[j]) : (bf16_t)0; }
;     } else {
;         const int r0 = rg * 16 + fq * 4;
;         u32x2 o; o.x = pk2(acc2[0], acc2[1]); o.y = pk2(acc2[2], (r0 + 3 < 255) ? acc2[3] : 0.f);
;         *(u32x2*)(WSP(bf16_t, WS_VCT) + ((size_t)bg * 128 + dcol) * 256 + r0) = o;
	ds_read_b128 v[0:3], v0 offset:8192
	ds_read_b128 v[4:7], v13 offset:16640
	s_add_u32 s2, s2, s20
	s_addc_u32 s3, s3, s21
	v_lshlrev_b32_e32 v214, 4, v33
	s_cmp_gt_u32 s13, 63
	s_waitcnt lgkmcnt(0)
	v_pk_add_f32 v[6:7], v[2:3], v[6:7]
	v_pk_add_f32 v[4:5], v[0:1], v[4:5]
	ds_read_b128 v[0:3], v13 offset:25088
	s_movk_i32 s13, 0xfc
	s_waitcnt lgkmcnt(0)
	v_pk_add_f32 v[6:7], v[6:7], v[2:3]
	v_pk_add_f32 v[4:5], v[4:5], v[0:1]
	ds_read_b128 v[0:3], v13 offset:33536
	s_waitcnt lgkmcnt(0)
	v_pk_add_f32 v[6:7], v[6:7], v[2:3]
	v_pk_add_f32 v[4:5], v[4:5], v[0:1]
	ds_read_b128 v[0:3], v13 offset:41984
	s_waitcnt lgkmcnt(0)
	v_pk_add_f32 v[6:7], v[6:7], v[2:3]
	v_pk_add_f32 v[4:5], v[4:5], v[0:1]
	ds_read_b128 v[0:3], v13 offset:50432
	s_waitcnt lgkmcnt(0)
	v_pk_add_f32 v[6:7], v[6:7], v[2:3]
	v_pk_add_f32 v[4:5], v[4:5], v[0:1]
	ds_read_b128 v[0:3], v13 offset:58880
	s_waitcnt lgkmcnt(0)
	v_pk_add_f32 v[8:9], v[4:5], v[0:1]
	v_add_u32_e32 v0, 0x10700, v13
	v_pk_add_f32 v[6:7], v[6:7], v[2:3]
	ds_read_b128 v[2:5], v0
	s_waitcnt lgkmcnt(0)
	v_pk_add_f32 v[2:3], v[8:9], v[2:3]
	v_pk_add_f32 v[0:1], v[6:7], v[4:5]
	v_mul_f32_e32 v4, 0x3d372713, v2
	v_mul_f32_e32 v5, 0x3d372713, v3
	v_mul_f32_e32 v4, v2, v4
	v_mul_f32_e32 v5, v3, v5
	v_fma_f32 v4, v2, v4, v2
	v_fma_f32 v5, v3, v5, v3
	v_mul_f32_e32 v4, 0x3f4c422a, v4
	v_mul_f32_e32 v5, 0x3f4c422a, v5
	v_add_f32_e32 v4, v4, v4
	v_add_f32_e32 v5, v5, v5
	v_mul_f32_e32 v4, 0x3fb8aa3b, v4
	v_mul_f32_e32 v5, 0x3fb8aa3b, v5
	v_exp_f32_e32 v4, v4
	v_exp_f32_e32 v5, v5
	v_pk_mul_f32 v[2:3], v[2:3], 0.5 op_sel_hi:[1,0]
	v_pk_add_f32 v[4:5], v[4:5], 1.0 op_sel_hi:[1,0]
	s_nop 0
	v_div_scale_f32 v6, s[20:21], v5, v5, 2.0
	v_rcp_f32_e32 v7, v6
	s_nop 0
	v_fma_f32 v8, -v6, v7, 1.0
	v_fmac_f32_e32 v7, v8, v7
	v_div_scale_f32 v8, vcc, 2.0, v5, 2.0
	v_mul_f32_e32 v9, v8, v7
	v_fma_f32 v13, -v6, v9, v8
	v_fmac_f32_e32 v9, v13, v7
	v_fma_f32 v6, -v6, v9, v8
	v_div_fmas_f32 v6, v6, v7, v9
	v_div_fixup_f32 v5, v6, v5, 2.0
	v_div_scale_f32 v6, s[20:21], v4, v4, 2.0
	v_rcp_f32_e32 v7, v6
	s_nop 0
	v_fma_f32 v8, -v6, v7, 1.0
	v_fmac_f32_e32 v7, v8, v7
	v_div_scale_f32 v8, vcc, 2.0, v4, 2.0
	v_mul_f32_e32 v9, v8, v7
	v_fma_f32 v13, -v6, v9, v8
	v_fmac_f32_e32 v9, v13, v7
	v_fma_f32 v6, -v6, v9, v8
	v_div_fmas_f32 v6, v6, v7, v9
	v_div_fixup_f32 v4, v6, v4, 2.0
	v_pk_add_f32 v[4:5], v[4:5], 1.0 op_sel_hi:[1,0] neg_lo:[1,0] neg_hi:[1,0]
	s_nop 0
	v_pk_add_f32 v[4:5], v[4:5], 1.0 op_sel_hi:[1,0]
	s_nop 0
	v_pk_mul_f32 v[2:3], v[2:3], v[4:5]
	s_nop 0
	v_cvt_pk_bf16_f32 v2, v2, v3
	v_mul_f32_e32 v3, 0x3d372713, v0
	v_mul_f32_e32 v3, v0, v3
	v_fma_f32 v3, v0, v3, v0
	v_mul_f32_e32 v3, 0x3f4c422a, v3
	v_add_f32_e32 v3, v3, v3
	v_mul_f32_e32 v3, 0x3fb8aa3b, v3
	v_exp_f32_e32 v4, v3
	v_mul_f32_e32 v3, 0x3d372713, v1
	v_mul_f32_e32 v3, v1, v3
	v_fma_f32 v3, v1, v3, v1
	v_mul_f32_e32 v3, 0x3f4c422a, v3
	v_add_f32_e32 v3, v3, v3
	v_mul_f32_e32 v3, 0x3fb8aa3b, v3
	v_exp_f32_e32 v5, v3
	v_pk_mul_f32 v[0:1], v[0:1], 0.5 op_sel_hi:[1,0]
	v_pk_add_f32 v[4:5], v[4:5], 1.0 op_sel_hi:[1,0]
	s_nop 0
	v_div_scale_f32 v3, s[20:21], v5, v5, 2.0
	v_rcp_f32_e32 v6, v3
	s_nop 0
	v_fma_f32 v7, -v3, v6, 1.0
	v_fmac_f32_e32 v6, v7, v6
	v_div_scale_f32 v7, vcc, 2.0, v5, 2.0
	v_mul_f32_e32 v8, v7, v6
	v_fma_f32 v9, -v3, v8, v7
	v_fmac_f32_e32 v8, v9, v6
	v_fma_f32 v3, -v3, v8, v7
	v_div_fmas_f32 v3, v3, v6, v8
	v_div_fixup_f32 v5, v3, v5, 2.0
	v_div_scale_f32 v3, s[20:21], v4, v4, 2.0
	v_rcp_f32_e32 v6, v3
	s_mov_b32 s20, s93
	v_fma_f32 v7, -v3, v6, 1.0
	v_fmac_f32_e32 v6, v7, v6
	v_div_scale_f32 v7, vcc, 2.0, v4, 2.0
	v_mul_f32_e32 v8, v7, v6
	v_fma_f32 v9, -v3, v8, v7
	v_fmac_f32_e32 v8, v9, v6
	v_fma_f32 v3, -v3, v8, v7
	v_div_fmas_f32 v3, v3, v6, v8
	v_div_fixup_f32 v4, v3, v4, 2.0
	v_pk_add_f32 v[4:5], v[4:5], 1.0 op_sel_hi:[1,0] neg_lo:[1,0] neg_hi:[1,0]
	s_nop 0
	v_pk_add_f32 v[4:5], v[4:5], 1.0 op_sel_hi:[1,0]
	s_nop 0
	v_pk_mul_f32 v[0:1], v[0:1], v[4:5]
	v_mul_u32_u24_e32 v4, 0x110, v54
	v_add3_u32 v16, 0, v4, v214
	v_or_b32_e32 v4, v34, v54
	v_ashrrev_i32_e32 v5, 31, v4
	v_cvt_pk_bf16_f32 v3, v0, v1
	v_lshlrev_b32_e32 v0, 8, v10
	v_lshlrev_b64 v[6:7], 8, v[4:5]
	v_sub_u32_e32 v0, v12, v0
	v_lshl_add_u64 v[6:7], s[2:3], 0, v[6:7]
	v_lshl_add_u32 v0, v11, 1, v0
	v_lshl_add_u64 v[14:15], v[6:7], 0, v[214:215]
	ds_write_b64 v0, v[2:3]
	s_waitcnt lgkmcnt(0)
	s_barrier
	global_load_dwordx4 v[10:13], v[14:15], off
	ds_read_b128 v[6:9], v16
	v_mov_b32_e32 v0, s20
	v_mov_b32_e32 v1, s20
	v_mov_b32_e32 v2, s20
	v_mov_b32_e32 v3, s20
	s_mov_b64 s[2:3], -1
	s_waitcnt vmcnt(0) lgkmcnt(0)
	v_mfma_f32_16x16x32_bf16 v[0:3], v[6:9], v[10:13], v[0:3]
	global_load_dwordx4 v[10:13], v[14:15], off offset:64
	ds_read_b128 v[6:9], v16 offset:64
	s_waitcnt vmcnt(0) lgkmcnt(0)
	v_mfma_f32_16x16x32_bf16 v[0:3], v[6:9], v[10:13], v[0:3]
	global_load_dwordx4 v[10:13], v[14:15], off offset:128
	ds_read_b128 v[6:9], v16 offset:128
	s_waitcnt vmcnt(0) lgkmcnt(0)
	v_mfma_f32_16x16x32_bf16 v[0:3], v[6:9], v[10:13], v[0:3]
	global_load_dwordx4 v[10:13], v[14:15], off offset:192
	ds_read_b128 v[6:9], v16 offset:192
	s_waitcnt vmcnt(0) lgkmcnt(0)
	v_mfma_f32_16x16x32_bf16 v[0:3], v[6:9], v[10:13], v[0:3]
	v_or_b32_e32 v6, s15, v32
	v_cmp_ne_u32_e32 vcc, s13, v6
	s_cbranch_scc0 .LBB0_587
	s_mov_b64 s[2:3], s[0:1]
	s_load_dwordx2 s[2:3], s[2:3], 0xd0
	s_mov_b64 s[20:21], 0x20858000
	v_lshlrev_b64 v[10:11], 9, v[4:5]
	s_nop 0
	v_cndmask_b32_e32 v7, 0, v3, vcc
	s_waitcnt lgkmcnt(0)
	s_add_u32 s2, s2, s20
	s_addc_u32 s3, s3, s21
	s_lshl_b32 s13, s14, 16
	s_add_u32 s2, s2, s13
	s_addc_u32 s3, s3, 0
	v_lshl_add_u64 v[10:11], s[2:3], 0, v[10:11]
	v_lshlrev_b32_e32 v214, 1, v6
	v_cvt_pk_bf16_f32 v8, v0, v1
	v_cvt_pk_bf16_f32 v9, v2, v7
	v_lshl_add_u64 v[10:11], v[10:11], 0, v[214:215]
	global_store_dwordx2 v[10:11], v[8:9], off
	s_mov_b64 s[2:3], 0

; #define TIDX opaque_tid()
; __device__ __forceinline__ unsigned pk2(float lo, float hi) { f32x2_t v = {lo, hi}; bf16x2_t b = __builtin_convertvector(v, bf16x2_t); return __builtin_bit_cast(unsigned, b); }
; __device__ __forceinline__ float ldnt(const float* p) { return __builtin_nontemporal_load(p); }
; __device__ __forceinline__ void lds_barrier() { asm volatile("s_waitcnt lgkmcnt(0)\n\ts_barrier" ::: "memory"); }
; #define WSP(T, off) ((T*)(__attribute__((address_space(1))) T*)(launder_ws(AWS, (off))))
; __device__ __forceinline__ void vtrans_item(const Args& a, int it, unsigned char* lds) {
;     const int which = it & 1, tile = (it >> 1) & 63, bg = it >> 7, b = bg >> 1, g = bg & 1;
;     const int col = (which ? C_NVW : C_NVS) + g * 128;
;     const float* Pp = WSP(const float, WS_P) + (size_t)(b * SEQ + tile * 64) * INP + col;
;     float* scr = (float*)lds;
;     const int tid = TIDX;
;     lds_barrier();
; #pragma unroll
;     for (int i = 0; i < 16; ++i) { const int idx = i * 512 + tid, tok = idx >> 7, d = idx & 127; scr[d * 65 + tok] = ldnt(Pp + (size_t)tok * INP + d); }
;     lds_barrier();
;     const int d = tid >> 2, seg = tid & 3;
;     const float* s = scr + d * 65 + seg * 16;
;     u32x4 o0, o1;
;     o0.x = pk2(s[0], s[1]); o0.y = pk2(s[2], s[3]); o0.z = pk2(s[4], s[5]); o0.w = pk2(s[6], s[7]);
;     o1.x = pk2(s[8], s[9]); o1.y = pk2(s[10], s[11]); o1.z = pk2(s[12], s[13]); o1.w = pk2(s[14], s[15]);
;     bf16_t* dst = WSP(bf16_t, which ? WS_VWT : WS_VST) + ((size_t)bg * 128 + d) * SEQ + tile * 64 + seg * 16;
;     *(u32x4*)dst = o0; *(u32x4*)(dst + 8) = o1;
.LBB0_622:
	s_and_b64 vcc, exec, s[2:3]
	s_cbranch_vccz .LBB0_624
	s_mov_b64 s[14:15], s[0:1]
	s_load_dwordx2 s[14:15], s[14:15], 0xd0
	s_add_i32 s2, s50, 0xfffffb00
	s_and_b32 s3, s50, 1
	s_and_b32 s13, s50, 0x80
	s_cmp_eq_u32 s3, 0
	s_movk_i32 s3, 0x600
	s_cselect_b32 s3, s3, 0x800
	s_mov_b32 s18, 0x20018000
	s_mov_b64 s[16:17], 0xec18000
	s_cselect_b32 s92, s18, 0x20418000
	s_or_b32 s13, s3, s13
	s_waitcnt lgkmcnt(0)
	s_add_u32 s14, s14, s16
	s_addc_u32 s15, s15, s17
	s_lshl_b32 s3, s2, 4
	s_and_b32 s16, s3, 0x1000
	s_lshl_b32 s3, s2, 5
	s_and_b32 s3, s3, 0xfc0
	s_or_b32 s16, s16, s3
	s_mulk_i32 s16, 0x7800
	s_add_u32 s14, s14, s16
	s_addc_u32 s15, s15, 0
	s_lshl_b32 s13, s13, 2
	v_mov_b32_e32 v4, v224
	s_add_u32 s14, s14, s13
	s_addc_u32 s15, s15, 0
	v_and_b32_e32 v2, 0x7f, v4
	v_lshlrev_b32_e32 v214, 2, v2
	v_lshl_add_u64 v[0:1], s[14:15], 0, v[214:215]
	s_movk_i32 s13, 0x104
	v_ashrrev_i32_e32 v6, 7, v4
	s_waitcnt lgkmcnt(0)
	s_barrier
	v_mad_u32_u24 v5, v2, s13, 0
	v_mad_i64_i32 v[14:15], s[14:15], v6, s95, v[0:1]
	v_lshl_add_u32 v13, v6, 2, v5
	v_ashrrev_i32_e32 v8, 2, v4
	s_and_b32 s16, s2, 0x180
	s_mov_b64 s[18:19], s[92:93]
	s_mov_b32 s17, s93
	global_load_dword v16, v[14:15], off nt
	v_add_co_u32_e32 v14, vcc, 0x1e000, v14
	s_nop 1
	v_addc_co_u32_e32 v15, vcc, 0, v15, vcc
	global_load_dword v17, v[14:15], off nt
	v_add_co_u32_e32 v14, vcc, 0x1e000, v14
	s_nop 1
	v_addc_co_u32_e32 v15, vcc, 0, v15, vcc
	global_load_dword v18, v[14:15], off nt
	v_add_co_u32_e32 v14, vcc, 0x1e000, v14
	s_nop 1
	v_addc_co_u32_e32 v15, vcc, 0, v15, vcc
	global_load_dword v19, v[14:15], off nt
	v_add_co_u32_e32 v14, vcc, 0x1e000, v14
	s_nop 1
	v_addc_co_u32_e32 v15, vcc, 0, v15, vcc
	global_load_dword v20, v[14:15], off nt
	v_add_co_u32_e32 v14, vcc, 0x1e000, v14
	s_nop 1
	v_addc_co_u32_e32 v15, vcc, 0, v15, vcc
	global_load_dword v21, v[14:15], off nt
	v_add_co_u32_e32 v14, vcc, 0x1e000, v14
	s_nop 1
	v_addc_co_u32_e32 v15, vcc, 0, v15, vcc
	global_load_dword v22, v[14:15], off nt
	v_add_co_u32_e32 v14, vcc, 0x1e000, v14
	s_nop 1
	v_addc_co_u32_e32 v15, vcc, 0, v15, vcc
	global_load_dword v23, v[14:15], off nt
	v_add_co_u32_e32 v14, vcc, 0x1e000, v14
	s_nop 1
	v_addc_co_u32_e32 v15, vcc, 0, v15, vcc
	global_load_dword v24, v[14:15], off nt
	v_add_co_u32_e32 v14, vcc, 0x1e000, v14
	s_nop 1
	v_addc_co_u32_e32 v15, vcc, 0, v15, vcc
	global_load_dword v25, v[14:15], off nt
	v_add_co_u32_e32 v14, vcc, 0x1e000, v14
	s_nop 1
	v_addc_co_u32_e32 v15, vcc, 0, v15, vcc
	global_load_dword v26, v[14:15], off nt
	v_add_co_u32_e32 v14, vcc, 0x1e000, v14
	s_nop 1
	v_addc_co_u32_e32 v15, vcc, 0, v15, vcc
	global_load_dword v27, v[14:15], off nt
	v_add_co_u32_e32 v14, vcc, 0x1e000, v14
	s_nop 1
	v_addc_co_u32_e32 v15, vcc, 0, v15, vcc
	global_load_dword v28, v[14:15], off nt
	v_add_co_u32_e32 v14, vcc, 0x1e000, v14
	s_nop 1
	v_addc_co_u32_e32 v15, vcc, 0, v15, vcc
	global_load_dword v29, v[14:15], off nt
	v_add_co_u32_e32 v14, vcc, 0x1e000, v14
	s_nop 1
	v_addc_co_u32_e32 v15, vcc, 0, v15, vcc
	global_load_dword v30, v[14:15], off nt
	v_add_co_u32_e32 v14, vcc, 0x1e000, v14
	s_nop 1
	v_addc_co_u32_e32 v15, vcc, 0, v15, vcc
	global_load_dword v31, v[14:15], off nt
	s_mov_b64 s[14:15], s[0:1]
	s_waitcnt vmcnt(15)
	ds_write_b32 v13, v16
	s_waitcnt vmcnt(14)
	ds_write_b32 v13, v17 offset:16
	s_waitcnt vmcnt(13)
	ds_write_b32 v13, v18 offset:32
	s_waitcnt vmcnt(12)
	ds_write_b32 v13, v19 offset:48
	s_waitcnt vmcnt(11)
	ds_write_b32 v13, v20 offset:64
	s_waitcnt vmcnt(10)
	ds_write_b32 v13, v21 offset:80
	s_waitcnt vmcnt(9)
	ds_write_b32 v13, v22 offset:96
	s_waitcnt vmcnt(8)
	ds_write_b32 v13, v23 offset:112
	s_waitcnt vmcnt(7)
	ds_write_b32 v13, v24 offset:128
	s_waitcnt vmcnt(6)
	ds_write_b32 v13, v25 offset:144
	s_waitcnt vmcnt(5)
	ds_write_b32 v13, v26 offset:160
	s_waitcnt vmcnt(4)
	ds_write_b32 v13, v27 offset:176
	s_waitcnt vmcnt(3)
	ds_write_b32 v13, v28 offset:192
	s_waitcnt vmcnt(2)
	ds_write_b32 v13, v29 offset:208
	s_waitcnt vmcnt(1)
	ds_write_b32 v13, v30 offset:224
	s_waitcnt vmcnt(0)
	ds_write_b32 v13, v31 offset:240
	v_lshlrev_b32_e32 v1, 4, v4
	v_and_b32_e32 v12, 48, v1
	v_mul_lo_u32 v0, v8, s13
	v_lshlrev_b32_e32 v1, 2, v12
	s_waitcnt lgkmcnt(0)
	s_barrier
	v_add3_u32 v9, 0, v0, v1
	ds_read2_b32 v[0:1], v9 offset1:1
	ds_read2_b32 v[2:3], v9 offset0:2 offset1:3
	ds_read2_b32 v[4:5], v9 offset0:6 offset1:7
	ds_read2_b32 v[10:11], v9 offset0:14 offset1:15
	ds_read2_b32 v[6:7], v9 offset0:10 offset1:11
	s_waitcnt lgkmcnt(4)
	v_cvt_pk_bf16_f32 v0, v0, v1
	s_waitcnt lgkmcnt(3)
	v_cvt_pk_bf16_f32 v1, v2, v3
	ds_read2_b32 v[2:3], v9 offset0:4 offset1:5
	v_lshlrev_b32_e32 v214, 1, v12
	s_waitcnt lgkmcnt(0)
	v_cvt_pk_bf16_f32 v2, v2, v3
	v_cvt_pk_bf16_f32 v3, v4, v5
	ds_read2_b32 v[4:5], v9 offset0:8 offset1:9
	s_waitcnt lgkmcnt(0)
	v_cvt_pk_bf16_f32 v4, v4, v5
	v_cvt_pk_bf16_f32 v5, v6, v7
	ds_read2_b32 v[6:7], v9 offset0:12 offset1:13
	s_load_dwordx2 s[14:15], s[14:15], 0xd0
	v_ashrrev_i32_e32 v9, 31, v8
	v_lshl_add_u64 v[8:9], v[8:9], 0, s[16:17]
	v_lshlrev_b64 v[8:9], 13, v[8:9]
	s_waitcnt lgkmcnt(0)
	s_add_u32 s14, s14, s18
	s_addc_u32 s15, s15, s19
	v_lshl_add_u64 v[8:9], s[14:15], 0, v[8:9]
	s_lshl_b32 s92, s3, 1
	v_lshl_add_u64 v[8:9], v[8:9], 0, s[92:93]
	v_lshl_add_u64 v[8:9], v[8:9], 0, v[214:215]
	v_cvt_pk_bf16_f32 v6, v6, v7
	v_cvt_pk_bf16_f32 v7, v10, v11
	global_store_dwordx4 v[8:9], v[0:3], off
	global_store_dwordx4 v[8:9], v[4:7], off offset:16

; __device__ __forceinline__ float siluf_(float x) { return x * __builtin_amdgcn_rcpf(1.f + __expf(-x)); }
; __device__ __forceinline__ float ldnt(const float* p) { return __builtin_nontemporal_load(p); }
; __device__ __forceinline__ void gdn_chunk(const Args& a, int l, int ci, unsigned char* lds) {
;     ...
;             const int sb = s0 + cg * 16;
;             float xm3 = sb >= 3 ? ldnt(P + ((size_t)(tb + cg * 16 - 3) * INP + col)) : 0.f;
;             float xm2 = sb >= 2 ? ldnt(P + ((size_t)(tb + cg * 16 - 2) * INP + col)) : 0.f;
;             float xm1 = sb >= 1 ? ldnt(P + ((size_t)(tb + cg * 16 - 1) * INP + col)) : 0.f;
; #pragma unroll
;             for (int i = 0; i < 16; ++i) {
;                 const float x = ldnt(P + ((size_t)(tb + cg * 16 + i) * INP + col));
;                 const float y = w0 * xm3 + w1 * xm2 + w2 * xm1 + w3 * x;
;                 dst[(cg * 16 + i) * 128 + d] = siluf_(y);
;                 xm3 = xm2; xm2 = xm1; xm1 = x;
;             }
.LBB0_655:
	s_or_b64 exec, exec, s[16:17]
	v_mad_i64_i32 v[74:75], s[14:15], v43, s95, 0
	v_mad_i64_i32 v[64:65], s[14:15], v50, s95, 0
	v_mad_i64_i32 v[62:63], s[14:15], v51, s95, 0
	v_mad_i64_i32 v[60:61], s[14:15], v52, s95, 0
	v_mad_i64_i32 v[58:59], s[14:15], v53, s95, 0
	v_mad_i64_i32 v[52:53], s[14:15], v76, s95, 0
	v_mad_i64_i32 v[50:51], s[14:15], v77, s95, 0
	v_lshl_add_u64 v[76:77], v[214:215], 2, s[2:3]
	v_lshl_add_u64 v[104:105], v[76:77], 0, v[74:75]
	v_mad_i64_i32 v[72:73], s[14:15], v44, s95, 0
	v_mad_i64_i32 v[70:71], s[14:15], v45, s95, 0
	v_mad_i64_i32 v[44:45], s[14:15], v101, s95, 0
	global_load_dword v106, v[104:105], off nt
	v_mad_i64_i32 v[68:69], s[14:15], v48, s95, 0
	v_mad_i64_i32 v[66:67], s[14:15], v49, s95, 0
	v_mad_i64_i32 v[48:49], s[14:15], v99, s95, 0
	s_waitcnt vmcnt(1)
	v_mul_f32_e32 v99, v80, v103
	v_fmac_f32_e32 v99, v47, v93
	v_fmac_f32_e32 v99, v79, v100
	s_nop 0
	v_mad_i64_i32 v[56:57], s[14:15], v54, s95, 0
	v_mad_i64_i32 v[54:55], s[14:15], v55, s95, 0
	v_mad_i64_i32 v[42:43], s[14:15], v102, s95, 0
	v_lshl_add_u64 v[124:125], v[76:77], 0, v[72:73]
	global_load_dword v107, v[124:125], off nt
	v_lshl_add_u64 v[126:127], v[76:77], 0, v[70:71]
	global_load_dword v108, v[126:127], off nt
	v_lshl_add_u64 v[128:129], v[76:77], 0, v[68:69]
	global_load_dword v109, v[128:129], off nt
	v_lshl_add_u64 v[130:131], v[76:77], 0, v[66:67]
	global_load_dword v110, v[130:131], off nt
	v_lshl_add_u64 v[132:133], v[76:77], 0, v[64:65]
	global_load_dword v111, v[132:133], off nt
	v_lshl_add_u64 v[134:135], v[76:77], 0, v[62:63]
	global_load_dword v112, v[134:135], off nt
	v_lshl_add_u64 v[136:137], v[76:77], 0, v[60:61]
	global_load_dword v113, v[136:137], off nt
	v_lshl_add_u64 v[138:139], v[76:77], 0, v[58:59]
	global_load_dword v114, v[138:139], off nt
	v_lshl_add_u64 v[140:141], v[76:77], 0, v[56:57]
	global_load_dword v115, v[140:141], off nt
	v_lshl_add_u64 v[142:143], v[76:77], 0, v[54:55]
	global_load_dword v116, v[142:143], off nt
	v_lshl_add_u64 v[144:145], v[76:77], 0, v[52:53]
	global_load_dword v117, v[144:145], off nt
	v_lshl_add_u64 v[146:147], v[76:77], 0, v[50:51]
	global_load_dword v118, v[146:147], off nt
	v_lshl_add_u64 v[148:149], v[76:77], 0, v[48:49]
	global_load_dword v119, v[148:149], off nt
	v_lshl_add_u64 v[150:151], v[76:77], 0, v[44:45]
	global_load_dword v120, v[150:151], off nt
	v_lshl_add_u64 v[152:153], v[76:77], 0, v[42:43]
	global_load_dword v121, v[152:153], off nt
	v_add_u32_e32 v214, 0xe00, v46
	v_add_co_u32_e32 v46, vcc, 0x1000, v40
	s_nop 0
	s_waitcnt vmcnt(15)
	v_fmac_f32_e32 v99, v81, v106
	v_mul_f32_e32 v93, 0xbfb8aa3b, v99
	v_exp_f32_e32 v93, v93
	s_nop 0
	v_add_f32_e32 v93, 1.0, v93
	v_rcp_f32_e32 v93, v93
	s_nop 0
	v_mul_f32_e32 v93, v99, v93
	ds_write_b32 v97, v93 offset:32768
	s_nop 0
	v_mul_f32_e32 v97, v80, v100
	v_fmac_f32_e32 v97, v47, v103
	v_fmac_f32_e32 v97, v79, v106
	s_nop 0
	s_waitcnt vmcnt(14)
	v_fmac_f32_e32 v97, v81, v107
	v_mul_f32_e32 v99, 0xbfb8aa3b, v97
	v_exp_f32_e32 v99, v99
	s_nop 0
	v_add_f32_e32 v99, 1.0, v99
	v_rcp_f32_e32 v99, v99
	s_nop 0
	v_mul_f32_e32 v97, v97, v99
	ds_write_b32 v98, v97 offset:32768
	s_nop 0
	s_nop 0
	v_mul_f32_e32 v97, v80, v106
	v_fmac_f32_e32 v97, v47, v100
	v_fmac_f32_e32 v97, v79, v107
	s_nop 0
	s_waitcnt vmcnt(13)
	v_fmac_f32_e32 v97, v81, v108
	v_mul_f32_e32 v99, 0xbfb8aa3b, v97
	v_exp_f32_e32 v99, v99
	s_nop 0
	v_add_f32_e32 v99, 1.0, v99
	v_rcp_f32_e32 v99, v99
	s_nop 0
	v_mul_f32_e32 v97, v97, v99
	ds_write_b32 v96, v97 offset:32768
	s_nop 0
	s_nop 0
	v_mul_f32_e32 v96, v80, v107
	v_fmac_f32_e32 v96, v47, v106
	v_fmac_f32_e32 v96, v79, v108
	s_nop 0
	s_waitcnt vmcnt(12)
	v_fmac_f32_e32 v96, v81, v109
	v_mul_f32_e32 v97, 0xbfb8aa3b, v96
	v_exp_f32_e32 v97, v97
	s_nop 0
	v_add_f32_e32 v97, 1.0, v97
	v_rcp_f32_e32 v97, v97
	s_nop 0
	v_mul_f32_e32 v96, v96, v97
	ds_write_b32 v94, v96 offset:32768
	s_nop 0
	s_nop 0
	v_mul_f32_e32 v94, v80, v108
	v_fmac_f32_e32 v94, v47, v107
	v_fmac_f32_e32 v94, v79, v109
	s_nop 0
	s_waitcnt vmcnt(11)
	v_fmac_f32_e32 v94, v81, v110
	v_mul_f32_e32 v93, 0xbfb8aa3b, v94
	v_exp_f32_e32 v93, v93
	s_nop 0
	v_add_f32_e32 v93, 1.0, v93
	v_rcp_f32_e32 v93, v93
	s_nop 0
	v_mul_f32_e32 v93, v94, v93
	ds_write_b32 v95, v93 offset:32768
	s_nop 0
	s_nop 0
	v_mul_f32_e32 v93, v80, v109
	v_fmac_f32_e32 v93, v47, v108
	v_fmac_f32_e32 v93, v79, v110
	s_nop 0
	s_waitcnt vmcnt(10)
; __device__ __forceinline__ float siluf_(float x) { return x * __builtin_amdgcn_rcpf(1.f + __expf(-x)); }
; __device__ __forceinline__ float ldnt(const float* p) { return __builtin_nontemporal_load(p); }
; __device__ __forceinline__ void gdn_chunk(const Args& a, int l, int ci, unsigned char* lds) {
;     ...
;             const int sb = s0 + cg * 16;
;             float xm3 = sb >= 3 ? ldnt(P + ((size_t)(tb + cg * 16 - 3) * INP + col)) : 0.f;
;             float xm2 = sb >= 2 ? ldnt(P + ((size_t)(tb + cg * 16 - 2) * INP + col)) : 0.f;
;             float xm1 = sb >= 1 ? ldnt(P + ((size_t)(tb + cg * 16 - 1) * INP + col)) : 0.f;
; #pragma unroll
;             for (int i = 0; i < 16; ++i) {
;                 const float x = ldnt(P + ((size_t)(tb + cg * 16 + i) * INP + col));
;                 const float y = w0 * xm3 + w1 * xm2 + w2 * xm1 + w3 * x;
;                 dst[(cg * 16 + i) * 128 + d] = siluf_(y);
;                 xm3 = xm2; xm2 = xm1; xm1 = x;
;             }
	v_fmac_f32_e32 v93, v81, v111
	v_mul_f32_e32 v95, 0xbfb8aa3b, v93
	v_exp_f32_e32 v95, v95
	s_nop 0
	v_add_f32_e32 v95, 1.0, v95
	v_rcp_f32_e32 v95, v95
	s_nop 0
	v_mul_f32_e32 v93, v93, v95
	ds_write_b32 v92, v93 offset:32768
	s_nop 0
	s_nop 0
	v_mul_f32_e32 v92, v80, v110
	v_fmac_f32_e32 v92, v47, v109
	v_fmac_f32_e32 v92, v79, v111
	s_nop 0
	s_waitcnt vmcnt(9)
	v_fmac_f32_e32 v92, v81, v112
	v_mul_f32_e32 v93, 0xbfb8aa3b, v92
	v_exp_f32_e32 v93, v93
	s_nop 0
	v_add_f32_e32 v93, 1.0, v93
	v_rcp_f32_e32 v93, v93
	s_nop 0
	v_mul_f32_e32 v92, v92, v93
	ds_write_b32 v90, v92 offset:32768
	s_nop 0
	s_nop 0
	v_mul_f32_e32 v90, v80, v111
	v_fmac_f32_e32 v90, v47, v110
	v_fmac_f32_e32 v90, v79, v112
	s_nop 0
	s_waitcnt vmcnt(8)
	v_fmac_f32_e32 v90, v81, v113
	v_mul_f32_e32 v93, 0xbfb8aa3b, v90
	v_exp_f32_e32 v93, v93
	s_nop 0
	v_add_f32_e32 v93, 1.0, v93
	v_rcp_f32_e32 v93, v93
	s_nop 0
	v_mul_f32_e32 v90, v90, v93
	ds_write_b32 v91, v90 offset:32768
	s_nop 0
	s_nop 0
	v_mul_f32_e32 v90, v80, v112
	v_fmac_f32_e32 v90, v47, v111
	v_fmac_f32_e32 v90, v79, v113
	s_nop 0
	s_waitcnt vmcnt(7)
	v_fmac_f32_e32 v90, v81, v114
	v_mul_f32_e32 v91, 0xbfb8aa3b, v90
	v_exp_f32_e32 v91, v91
	s_nop 0
	v_add_f32_e32 v91, 1.0, v91
	v_rcp_f32_e32 v91, v91
	s_nop 0
	v_mul_f32_e32 v90, v90, v91
	ds_write_b32 v89, v90 offset:32768
	s_nop 0
	s_nop 0
	v_mul_f32_e32 v89, v80, v113
	v_fmac_f32_e32 v89, v47, v112
	v_fmac_f32_e32 v89, v79, v114
	s_nop 0
	s_waitcnt vmcnt(6)
	v_fmac_f32_e32 v89, v81, v115
	v_mul_f32_e32 v91, 0xbfb8aa3b, v89
	v_exp_f32_e32 v91, v91
	s_nop 0
	v_add_f32_e32 v91, 1.0, v91
	v_rcp_f32_e32 v91, v91
	s_nop 0
	v_mul_f32_e32 v89, v89, v91
	ds_write_b32 v88, v89 offset:32768
	s_nop 0
	s_nop 0
	v_mul_f32_e32 v88, v80, v114
	v_fmac_f32_e32 v88, v47, v113
	v_fmac_f32_e32 v88, v79, v115
	s_nop 0
	s_waitcnt vmcnt(5)
	v_fmac_f32_e32 v88, v81, v116
	v_mul_f32_e32 v89, 0xbfb8aa3b, v88
	v_exp_f32_e32 v89, v89
	s_nop 0
	v_add_f32_e32 v89, 1.0, v89
	v_rcp_f32_e32 v89, v89
	s_nop 0
	v_mul_f32_e32 v88, v88, v89
	ds_write_b32 v87, v88 offset:32768
	s_nop 0
	s_nop 0
	v_mul_f32_e32 v87, v80, v115
	v_fmac_f32_e32 v87, v47, v114
	v_fmac_f32_e32 v87, v79, v116
	s_nop 0
	s_waitcnt vmcnt(4)
	v_fmac_f32_e32 v87, v81, v117
	v_mul_f32_e32 v89, 0xbfb8aa3b, v87
	v_exp_f32_e32 v89, v89
	s_nop 0
	v_add_f32_e32 v89, 1.0, v89
	v_rcp_f32_e32 v89, v89
	s_nop 0
	v_mul_f32_e32 v87, v87, v89
	ds_write_b32 v86, v87 offset:32768
	s_nop 0
	s_nop 0
	v_mul_f32_e32 v86, v80, v116
	v_fmac_f32_e32 v86, v47, v115
	v_fmac_f32_e32 v86, v79, v117
	s_nop 0
	s_waitcnt vmcnt(3)
	v_fmac_f32_e32 v86, v81, v118
	v_mul_f32_e32 v87, 0xbfb8aa3b, v86
	v_exp_f32_e32 v87, v87
	s_nop 0
	v_add_f32_e32 v87, 1.0, v87
	v_rcp_f32_e32 v87, v87
	s_nop 0
	v_mul_f32_e32 v86, v86, v87
	ds_write_b32 v85, v86 offset:32768
	s_nop 0
	s_nop 0
	v_mul_f32_e32 v85, v80, v117
	v_fmac_f32_e32 v85, v47, v116
	v_fmac_f32_e32 v85, v79, v118
	s_nop 0
	s_waitcnt vmcnt(2)
	v_fmac_f32_e32 v85, v81, v119
	v_mul_f32_e32 v87, 0xbfb8aa3b, v85
	v_exp_f32_e32 v87, v87
	s_nop 0
	v_add_f32_e32 v87, 1.0, v87
	v_rcp_f32_e32 v87, v87
	s_nop 0
	v_mul_f32_e32 v85, v85, v87
	ds_write_b32 v84, v85 offset:32768
	s_nop 0
	s_nop 0
	s_nop 0
	s_nop 0
	v_mul_f32_e32 v85, v80, v118
	v_mul_f32_e32 v77, v80, v119
	v_fmac_f32_e32 v85, v47, v117
	v_fmac_f32_e32 v77, v47, v118
	v_fmac_f32_e32 v85, v79, v119
	s_nop 0
	s_waitcnt vmcnt(1)
	v_fmac_f32_e32 v77, v79, v120
	v_fmac_f32_e32 v85, v81, v120
	s_nop 0
	s_waitcnt vmcnt(0)
	v_fmac_f32_e32 v77, v81, v121
	v_mul_f32_e32 v87, 0xbfb8aa3b, v85
	v_mul_f32_e32 v47, 0xbfb8aa3b, v77
	v_exp_f32_e32 v87, v87
	v_exp_f32_e32 v47, v47
	v_add_f32_e32 v87, 1.0, v87
	v_add_f32_e32 v47, 1.0, v47
	v_rcp_f32_e32 v87, v87
	v_rcp_f32_e32 v47, v47
	v_mul_f32_e32 v85, v85, v87
	v_mul_f32_e32 v47, v77, v47
	ds_write_b32 v83, v85 offset:32768
	ds_write_b32 v82, v47 offset:32768
	v_addc_co_u32_e32 v47, vcc, 0, v41, vcc
	v_add_co_u32_e32 v76, vcc, 0x3000, v40
	global_load_dword v46, v[46:47], off offset:1024
	s_nop 0
	v_addc_co_u32_e32 v77, vcc, 0, v41, vcc
	global_load_dword v47, v[76:77], off offset:512
	v_add_co_u32_e32 v76, vcc, 0x5000, v40
	s_nop 1
	v_addc_co_u32_e32 v77, vcc, 0, v41, vcc
	v_add_co_u32_e32 v40, vcc, 0x6000, v40
	global_load_dword v76, v[76:77], off
	s_nop 0
	v_addc_co_u32_e32 v41, vcc, 0, v41, vcc
	global_load_dword v40, v[40:41], off offset:3584
	v_mov_b32_e32 v41, 0
	v_mov_b32_e32 v77, 0
	s_and_saveexec_b64 s[16:17], s[40:41]
	s_cbranch_execz .LBB0_784
	v_lshl_add_u64 v[34:35], v[214:215], 2, v[34:35]
	global_load_dword v77, v[34:35], off nt
	s_or_b64 exec, exec, s[16:17]
	s_and_saveexec_b64 s[16:17], s[42:43]
	s_cbranch_execnz .LBB0_785
